# attention: loop-invariant V^T LDS addresses hoisted to 35 spare VGPRs; gemm prologues issue K-tile 1 staging before the first wait; MFMA/VALU wait states re-derived after deletions (5 s_nop)
# baseline (speedup 1.0000x reference)
.LBB0_118:
	s_lshl_b32 s1, s1, 5
	s_mov_b64 s[10:11], 0x80
	s_and_b32 s1, s1, 0x60
	s_add_i32 m0, s34, 0x18000
	v_lshl_add_u64 v[6:7], v[6:7], 0, s[10:11]
	s_ashr_i32 s39, s52, 31
	s_ashr_i32 s40, s74, 31
	s_lshl_b32 s5, s0, 13
	s_lshl_b32 s13, s1, 7
	global_load_lds_dwordx4 v[6:7], off
	v_lshl_add_u64 v[4:5], v[4:5], 0, s[10:11]
	s_add_i32 m0, s34, 0x1a000
	s_add_i32 s41, s34, 0x8000
	s_add_i32 s42, s34, 0xa000
	global_load_lds_dwordx4 v[4:5], off
	v_lshl_add_u64 v[0:1], v[0:1], 0, s[10:11]
	s_mov_b32 m0, s41
	s_add_u32 s16, s26, 0x40080
	global_load_lds_dwordx4 v[0:1], off
	v_lshl_add_u64 v[0:1], v[2:3], 0, s[10:11]
	s_mov_b32 m0, s42
	s_addc_u32 s17, s27, 0
	global_load_lds_dwordx4 v[0:1], off
	s_add_i32 m0, s34, 0x1c000
	v_lshl_add_u64 v[0:1], s[16:17], 0, v[138:139]
	global_load_lds_dwordx4 v[0:1], off
	v_lshl_add_u64 v[0:1], s[16:17], 0, v[142:143]
	s_add_i32 m0, s34, 0x1e000
	v_lshlrev_b32_e32 v2, 6, v171
	global_load_lds_dwordx4 v[0:1], off
	s_waitcnt vmcnt(8)
	s_barrier
	v_and_b32_e32 v0, 15, v171
	v_lshlrev_b32_e32 v1, 1, v11
	s_movk_i32 s14, 0x3c0
	v_lshlrev_b32_e32 v3, 2, v171
	v_and_or_b32 v2, v2, s14, v1
	v_and_b32_e32 v3, 32, v3
	v_lshl_or_b32 v158, s0, 6, v0
	v_lshl_or_b32 v0, v0, 6, v1
	v_lshlrev_b32_e32 v1, 8, v171
	v_bitop3_b32 v159, s13, v2, v3 bitop3:0xf6
	v_and_b32_e32 v1, 0x38000, v1
	v_lshlrev_b32_e32 v2, 11, v10
	v_or3_b32 v1, v8, v1, v2
	v_add_u32_e32 v144, v1, v9
	v_lshlrev_b32_e32 v1, 4, v12
	s_waitcnt vmcnt(6)
	s_cmpk_lt_u32 s12, 0x100
	v_and_b32_e32 v1, 0x78000, v1
	v_bitop3_b32 v0, v0, s5, v3 bitop3:0xde
	s_cselect_b64 s[12:13], -1, 0
	v_or3_b32 v1, v8, v1, v2
	s_add_i32 s44, 0, 0x10000
	s_add_i32 s45, 0, 0x14000
	s_mov_b32 s43, s52
	v_or_b32_e32 v160, s1, v11
	v_mov_b32_e32 v145, v139
	v_add_u32_e32 v146, v1, v9
	v_mov_b32_e32 v147, v139
	v_mov_b64_e32 v[148:149], 0x500
	v_mov_b64_e32 v[150:151], 0x4ff
	v_add_u32_e32 v161, s44, v159
	v_add_u32_e32 v162, s45, v159
	v_add_u32_e32 v163, 0, v0
	s_mov_b32 s14, 0x3db504f3
	s_barrier
	s_branch .LBB0_121

.LBB0_284:
	s_waitcnt vmcnt(3)
	v_mov_b64_e32 v[66:67], v[34:35]
	v_mov_b64_e32 v[64:65], v[32:33]
	s_waitcnt vmcnt(1)
	v_mov_b64_e32 v[70:71], v[38:39]
	v_mov_b64_e32 v[68:69], v[36:37]
	v_and_b32_e32 v34, 0xffff0000, v64
	v_and_b32_e32 v35, 0xffff0000, v68
	v_mul_f32_e64 v32, |v34|, s45
	v_exp_f32_e32 v33, v32
	v_mul_f32_e64 v32, |v35|, s45
	v_exp_f32_e32 v32, v32
	v_cmp_le_f32_e64 s[4:5], 0, v34
	v_add_f32_e32 v36, 1.0, v33
	v_rcp_f32_e32 v123, v36
	v_add_f32_e32 v36, 1.0, v32
	v_rcp_f32_e32 v122, v36
	v_cmp_le_f32_e64 s[6:7], 0, v35
	v_lshlrev_b32_e32 v37, 16, v65
	v_pk_mul_f32 v[124:125], v[32:33], v[122:123]
	v_lshlrev_b32_e32 v36, 16, v69
	v_cndmask_b32_e64 v33, v125, v123, s[4:5]
	v_cndmask_b32_e64 v32, v124, v122, s[6:7]
	v_pk_fma_f32 v[32:33], v[98:99], v[32:33], v[120:121]
	v_cmp_le_f32_e64 s[8:9], 0, v37
	v_mul_f32_e32 v32, v32, v33
	v_cmp_le_f32_e64 s[10:11], 0, v36
	v_lshlrev_b32_e32 v68, 16, v68
	v_mul_f32_dpp v32, v32, v32 row_shr:1 row_mask:0xf bank_mask:0xf
	v_lshlrev_b32_e32 v64, 16, v64
	v_cndmask_b32_e64 v123, v123, v125, s[4:5]
	v_mul_f32_dpp v32, v32, v32 row_shr:2 row_mask:0xf bank_mask:0xf
	v_cndmask_b32_e64 v122, v122, v124, s[6:7]
	v_pk_mul_f32 v[122:123], v[98:99], v[122:123]
	v_mul_f32_dpp v32, v32, v32 row_shr:4 row_mask:0xf bank_mask:0xf
	s_nop 1
	v_mul_f32_dpp v32, v32, v32 row_shr:8 row_mask:0xf bank_mask:0xf
	v_mov_b32_e32 v34, 1.0
	s_nop 1
	v_mov_b32_dpp v34, v32 row_bcast:15 row_mask:0xa bank_mask:0xf
	v_mul_f32_e32 v74, v32, v34
	v_mul_f32_e64 v34, |v37|, s45
	v_exp_f32_e32 v35, v34
	v_mul_f32_e64 v34, |v36|, s45
	v_exp_f32_e32 v34, v34
	v_mov_b32_e32 v32, 1.0
	v_add_f32_e32 v38, 1.0, v35
	v_rcp_f32_e32 v127, v38
	v_add_f32_e32 v38, 1.0, v34
	v_rcp_f32_e32 v126, v38
	v_mov_b32_dpp v32, v74 wave_shr:1 row_mask:0xf bank_mask:0xf
	v_cndmask_b32_e64 v32, v32, 1.0, s[0:1]
	v_mul_f32_e32 v56, v33, v32
	v_pk_mul_f32 v[128:129], v[34:35], v[126:127]
	v_cndmask_b32_e64 v33, v129, v127, s[8:9]
	v_cndmask_b32_e64 v32, v128, v126, s[10:11]
	v_pk_fma_f32 v[32:33], v[96:97], v[32:33], v[114:115]
	v_and_b32_e32 v36, 0xffff0000, v65
	v_mul_f32_e32 v32, v32, v33
	v_and_b32_e32 v37, 0xffff0000, v69
	v_cmp_le_f32_e64 s[12:13], 0, v36
	v_mul_f32_dpp v32, v32, v32 row_shr:1 row_mask:0xf bank_mask:0xf
	v_cmp_le_f32_e64 s[14:15], 0, v37
	v_rcp_f32_e32 v65, v56
	v_mul_f32_dpp v32, v32, v32 row_shr:2 row_mask:0xf bank_mask:0xf
	v_mul_f32_e64 v56, |v64|, s45
	v_exp_f32_e32 v56, v56
	v_mul_f32_dpp v32, v32, v32 row_shr:4 row_mask:0xf bank_mask:0xf
	v_add_f32_e32 v168, 1.0, v56
	v_rcp_f32_e32 v168, v168
	v_mul_f32_dpp v32, v32, v32 row_shr:8 row_mask:0xf bank_mask:0xf
	v_mov_b32_e32 v34, 1.0
	v_readlane_b32 s42, v74, 31
	v_readlane_b32 s50, v74, 63
	v_mov_b32_dpp v34, v32 row_bcast:15 row_mask:0xa bank_mask:0xf
	v_mul_f32_e32 v164, v32, v34
	v_mul_f32_e64 v34, |v36|, s45
	v_exp_f32_e32 v35, v34
	v_mul_f32_e64 v34, |v37|, s45
	v_exp_f32_e32 v34, v34
	v_mov_b32_e32 v32, 1.0
	v_add_f32_e32 v38, 1.0, v35
	v_rcp_f32_e32 v131, v38
	v_add_f32_e32 v38, 1.0, v34
	v_rcp_f32_e32 v130, v38
	v_mov_b32_dpp v32, v164 wave_shr:1 row_mask:0xf bank_mask:0xf
	v_cndmask_b32_e64 v32, v32, 1.0, s[0:1]
	v_mul_f32_e32 v57, v33, v32
	v_pk_mul_f32 v[132:133], v[34:35], v[130:131]
	v_cndmask_b32_e64 v33, v133, v131, s[12:13]
	v_cndmask_b32_e64 v32, v132, v130, s[14:15]
	v_pk_fma_f32 v[32:33], v[94:95], v[32:33], v[112:113]
	v_lshlrev_b32_e32 v37, 16, v66
	v_mul_f32_e32 v32, v32, v33
	v_lshlrev_b32_e32 v36, 16, v70
	v_readlane_b32 s16, v164, 31
	v_mul_f32_dpp v32, v32, v32 row_shr:1 row_mask:0xf bank_mask:0xf
	v_readlane_b32 s17, v164, 63
	v_rcp_f32_e32 v69, v57
	v_mul_f32_dpp v32, v32, v32 row_shr:2 row_mask:0xf bank_mask:0xf
	v_mul_f32_e64 v57, |v68|, s45
	v_exp_f32_e32 v57, v57
	v_mul_f32_dpp v32, v32, v32 row_shr:4 row_mask:0xf bank_mask:0xf
	v_add_f32_e32 v169, 1.0, v57
	v_rcp_f32_e32 v169, v169
	v_mul_f32_dpp v32, v32, v32 row_shr:8 row_mask:0xf bank_mask:0xf
	v_mov_b32_e32 v34, 1.0
	v_pk_mul_f32 v[56:57], v[56:57], v[168:169]
	s_nop 0
	v_mov_b32_dpp v34, v32 row_bcast:15 row_mask:0xa bank_mask:0xf
	v_mul_f32_e32 v166, v32, v34
	v_mov_b32_e32 v32, 1.0
	v_readlane_b32 s18, v166, 31
	v_readlane_b32 s19, v166, 63
	v_mov_b32_dpp v32, v166 wave_shr:1 row_mask:0xf bank_mask:0xf
	v_cndmask_b32_e64 v32, v32, 1.0, s[0:1]
	v_mul_f32_e32 v165, v33, v32
	v_mul_f32_e64 v32, |v37|, s45
	v_exp_f32_e32 v33, v32
	v_mul_f32_e64 v32, |v36|, s45
	v_exp_f32_e32 v32, v32
	v_mov_b32_e32 v34, s19
	v_mov_b32_e32 v35, s18
	v_cndmask_b32_e64 v59, v34, v35, s[2:3]
	v_add_f32_e32 v34, 1.0, v33
	v_rcp_f32_e32 v135, v34
	v_add_f32_e32 v34, 1.0, v32
	v_rcp_f32_e32 v134, v34
	v_mov_b32_e32 v34, s17
	v_mov_b32_e32 v35, s16
	v_cmp_le_f32_e64 s[16:17], 0, v37
	v_pk_mul_f32 v[136:137], v[32:33], v[134:135]
	v_cmp_le_f32_e64 s[18:19], 0, v36
	v_cndmask_b32_e64 v33, v137, v135, s[16:17]
	v_cndmask_b32_e64 v58, v34, v35, s[2:3]
	v_cndmask_b32_e64 v32, v136, v134, s[18:19]
	v_pk_fma_f32 v[32:33], v[92:93], v[32:33], v[110:111]
	v_mul_f32_e32 v32, v32, v33
	v_and_b32_e32 v36, 0xffff0000, v66
	v_and_b32_e32 v37, 0xffff0000, v70
	v_mul_f32_dpp v32, v32, v32 row_shr:1 row_mask:0xf bank_mask:0xf
	v_cmp_le_f32_e64 s[20:21], 0, v36
	v_cmp_le_f32_e64 s[22:23], 0, v37
	v_mul_f32_dpp v32, v32, v32 row_shr:2 row_mask:0xf bank_mask:0xf
	v_rcp_f32_e32 v165, v165
	s_nop 0
	v_mul_f32_dpp v32, v32, v32 row_shr:4 row_mask:0xf bank_mask:0xf
	s_nop 1
	v_mul_f32_dpp v32, v32, v32 row_shr:8 row_mask:0xf bank_mask:0xf
	v_mov_b32_e32 v34, 1.0
	s_nop 1
	v_mov_b32_dpp v34, v32 row_bcast:15 row_mask:0xa bank_mask:0xf
	v_mul_f32_e32 v172, v32, v34
	v_mul_f32_e64 v34, |v36|, s45
	v_exp_f32_e32 v35, v34
	v_mul_f32_e64 v34, |v37|, s45
	v_exp_f32_e32 v34, v34
	v_mov_b32_e32 v32, 1.0
	v_add_f32_e32 v38, 1.0, v35
	v_rcp_f32_e32 v139, v38
	v_add_f32_e32 v38, 1.0, v34
	v_rcp_f32_e32 v138, v38
	v_mov_b32_dpp v32, v172 wave_shr:1 row_mask:0xf bank_mask:0xf
	v_cndmask_b32_e64 v32, v32, 1.0, s[0:1]
	v_mul_f32_e32 v167, v33, v32
	v_pk_mul_f32 v[140:141], v[34:35], v[138:139]
	v_cndmask_b32_e64 v33, v141, v139, s[20:21]
	v_cndmask_b32_e64 v32, v140, v138, s[22:23]
	v_pk_fma_f32 v[32:33], v[90:91], v[32:33], v[108:109]
	v_lshlrev_b32_e32 v37, 16, v67
	v_mul_f32_e32 v32, v32, v33
	v_lshlrev_b32_e32 v36, 16, v71
	v_readlane_b32 s24, v172, 31
	v_mul_f32_dpp v32, v32, v32 row_shr:1 row_mask:0xf bank_mask:0xf
	v_readlane_b32 s25, v172, 63
	v_rcp_f32_e32 v167, v167
	v_mul_f32_dpp v32, v32, v32 row_shr:2 row_mask:0xf bank_mask:0xf
	s_nop 1
	v_mul_f32_dpp v32, v32, v32 row_shr:4 row_mask:0xf bank_mask:0xf
	s_nop 1
	v_mul_f32_dpp v32, v32, v32 row_shr:8 row_mask:0xf bank_mask:0xf
	v_mov_b32_e32 v34, 1.0
	s_nop 1
	v_mov_b32_dpp v34, v32 row_bcast:15 row_mask:0xa bank_mask:0xf
	v_mul_f32_e32 v174, v32, v34
	v_mov_b32_e32 v32, 1.0
	v_readlane_b32 s26, v174, 31
	v_readlane_b32 s27, v174, 63
	v_mov_b32_dpp v32, v174 wave_shr:1 row_mask:0xf bank_mask:0xf
	v_cndmask_b32_e64 v32, v32, 1.0, s[0:1]
	v_mul_f32_e32 v173, v33, v32
	v_mul_f32_e64 v32, |v37|, s45
	v_exp_f32_e32 v33, v32
	v_mul_f32_e64 v32, |v36|, s45
	v_exp_f32_e32 v32, v32
	v_mov_b32_e32 v34, s27
	v_mov_b32_e32 v35, s26
	v_cndmask_b32_e64 v61, v34, v35, s[2:3]
	v_add_f32_e32 v34, 1.0, v33
	v_rcp_f32_e32 v161, v34
	v_add_f32_e32 v34, 1.0, v32
	v_rcp_f32_e32 v160, v34
	v_mov_b32_e32 v34, s25
	v_mov_b32_e32 v35, s24
	v_cmp_le_f32_e64 s[24:25], 0, v37
	v_pk_mul_f32 v[162:163], v[32:33], v[160:161]
	v_cmp_le_f32_e64 s[26:27], 0, v36
	v_cndmask_b32_e64 v33, v163, v161, s[24:25]
	v_cndmask_b32_e64 v60, v34, v35, s[2:3]
	v_cndmask_b32_e64 v32, v162, v160, s[26:27]
	v_pk_fma_f32 v[32:33], v[88:89], v[32:33], v[106:107]
	v_mul_f32_e32 v32, v32, v33
	v_and_b32_e32 v36, 0xffff0000, v67
	v_and_b32_e32 v37, 0xffff0000, v71
	v_mul_f32_dpp v32, v32, v32 row_shr:1 row_mask:0xf bank_mask:0xf
	v_cmp_le_f32_e64 s[28:29], 0, v36
	v_cmp_le_f32_e64 s[30:31], 0, v37
	v_mul_f32_dpp v32, v32, v32 row_shr:2 row_mask:0xf bank_mask:0xf
	v_rcp_f32_e32 v173, v173
	s_nop 0
	v_mul_f32_dpp v32, v32, v32 row_shr:4 row_mask:0xf bank_mask:0xf
	s_nop 1
	v_mul_f32_dpp v32, v32, v32 row_shr:8 row_mask:0xf bank_mask:0xf
	v_mov_b32_e32 v34, 1.0
	s_nop 1
	v_mov_b32_dpp v34, v32 row_bcast:15 row_mask:0xa bank_mask:0xf
	v_mul_f32_e32 v176, v32, v34
	v_mul_f32_e64 v34, |v36|, s45
	v_exp_f32_e32 v35, v34
	v_mul_f32_e64 v34, |v37|, s45
	v_exp_f32_e32 v34, v34
	v_mov_b32_e32 v32, 1.0
	v_add_f32_e32 v38, 1.0, v35
	v_rcp_f32_e32 v67, v38
	v_add_f32_e32 v38, 1.0, v34
	v_rcp_f32_e32 v66, v38
	v_mov_b32_dpp v32, v176 wave_shr:1 row_mask:0xf bank_mask:0xf
	v_cndmask_b32_e64 v32, v32, 1.0, s[0:1]
	v_mul_f32_e32 v175, v33, v32
	v_pk_mul_f32 v[70:71], v[34:35], v[66:67]
	v_cndmask_b32_e64 v33, v71, v67, s[28:29]
	v_cndmask_b32_e64 v32, v70, v66, s[30:31]
	v_pk_fma_f32 v[32:33], v[86:87], v[32:33], v[104:105]
	v_readlane_b32 s34, v176, 31
	v_mul_f32_e32 v32, v32, v33
	v_readlane_b32 s35, v176, 63
	v_add_u32_e32 v38, s33, v158
	v_mul_f32_dpp v32, v32, v32 row_shr:1 row_mask:0xf bank_mask:0xf
	v_rcp_f32_e32 v175, v175
	v_cndmask_b32_e64 v67, v67, v71, s[28:29]
	v_mul_f32_dpp v32, v32, v32 row_shr:2 row_mask:0xf bank_mask:0xf
	v_cndmask_b32_e64 v66, v66, v70, s[30:31]
	v_pk_mul_f32 v[66:67], v[86:87], v[66:67]
	v_mul_f32_dpp v32, v32, v32 row_shr:4 row_mask:0xf bank_mask:0xf
	s_nop 1
	v_mul_f32_dpp v32, v32, v32 row_shr:8 row_mask:0xf bank_mask:0xf
	v_mov_b32_e32 v34, 1.0
	s_nop 1
	v_mov_b32_dpp v34, v32 row_bcast:15 row_mask:0xa bank_mask:0xf
	v_mul_f32_e32 v180, v32, v34
	v_mov_b32_e32 v32, 1.0
	v_readlane_b32 s36, v180, 31
	v_readlane_b32 s37, v180, 63
	v_mov_b32_dpp v32, v180 wave_shr:1 row_mask:0xf bank_mask:0xf
	v_cndmask_b32_e64 v32, v32, 1.0, s[0:1]
	v_mul_f32_e32 v177, v33, v32
	v_mov_b32_e32 v32, s37
	v_mov_b32_e32 v33, s36
	v_cndmask_b32_e64 v63, v32, v33, s[2:3]
	v_mov_b32_e32 v32, s35
	v_mov_b32_e32 v33, s34
	v_cndmask_b32_e64 v62, v32, v33, s[2:3]
	v_add_u32_e32 v32, 0x400, v38
	v_add_u32_e32 v33, 1, v159
	v_cndmask_b32_e32 v32, v33, v32, vcc
	v_ashrrev_i32_e32 v33, 31, v32
	v_lshlrev_b64 v[32:33], 13, v[32:33]
	v_lshl_add_u64 v[34:35], v[116:117], 0, v[32:33]
	v_lshl_add_u64 v[36:37], v[118:119], 0, v[32:33]
	global_load_dwordx4 v[32:35], v[34:35], off offset:2048
	s_nop 0
	global_load_dwordx4 v[40:43], v[36:37], off
	v_add_u32_e32 v36, 0x401, v38
	v_cndmask_b32_e32 v36, v159, v36, vcc
	v_ashrrev_i32_e32 v37, 31, v36
	v_lshlrev_b64 v[36:37], 13, v[36:37]
	v_lshl_add_u64 v[38:39], v[116:117], 0, v[36:37]
	v_lshl_add_u64 v[44:45], v[118:119], 0, v[36:37]
	global_load_dwordx4 v[36:39], v[38:39], off offset:2048
	s_nop 0
	global_load_dwordx4 v[44:47], v[44:45], off
	v_cmp_le_f32_e64 s[34:35], 0, v68
	v_cmp_le_f32_e64 s[36:37], 0, v64
	s_nop 0
	v_cndmask_b32_e64 v179, v169, v57, s[34:35]
	v_cndmask_b32_e64 v178, v168, v56, s[36:37]
	v_cndmask_b32_e64 v57, v57, v169, s[34:35]
	v_cndmask_b32_e64 v56, v56, v168, s[36:37]
	v_pk_fma_f32 v[56:57], v[100:101], v[56:57], v[102:103]
	v_pk_mul_f32 v[168:169], v[100:101], v[178:179]
	v_mul_f32_e32 v57, v57, v56
	v_mov_b32_e32 v68, s42
	v_rcp_f32_e32 v177, v177
	v_mul_f32_dpp v57, v57, v57 row_shr:1 row_mask:0xf bank_mask:0xf
	s_nop 1
	v_mul_f32_dpp v57, v57, v57 row_shr:2 row_mask:0xf bank_mask:0xf
	s_nop 1
	v_mul_f32_dpp v57, v57, v57 row_shr:4 row_mask:0xf bank_mask:0xf
	s_nop 1
	v_mul_f32_dpp v57, v57, v57 row_shr:8 row_mask:0xf bank_mask:0xf
	v_mov_b32_e32 v64, 1.0
	s_nop 1
	v_mov_b32_dpp v64, v57 row_bcast:15 row_mask:0xa bank_mask:0xf
	v_mul_f32_e32 v64, v57, v64
	v_mov_b32_e32 v57, 1.0
	v_readlane_b32 s34, v64, 31
	v_readlane_b32 s35, v64, 63
	v_mov_b32_dpp v57, v64 wave_shr:1 row_mask:0xf bank_mask:0xf
	v_cndmask_b32_e64 v57, v57, 1.0, s[0:1]
	v_mul_f32_e32 v56, v56, v57
	v_rcp_f32_e32 v178, v56
	v_rcp_f32_e32 v179, v64
	v_mov_b32_e32 v56, s35
	v_mov_b32_e32 v64, s34
	v_cndmask_b32_e64 v56, v56, v64, s[2:3]
	v_rcp_f32_e32 v64, v74
	v_mov_b32_e32 v57, s50
	v_cndmask_b32_e64 v57, v57, v68, s[2:3]
	v_rcp_f32_e32 v68, v164
	v_pk_mul_f32 v[64:65], v[122:123], v[64:65]
	v_cndmask_b32_e64 v123, v127, v129, s[8:9]
	v_cndmask_b32_e64 v122, v126, v128, s[10:11]
	v_rcp_f32_e32 v164, v166
	v_pk_mul_f32 v[122:123], v[96:97], v[122:123]
	v_rcp_f32_e32 v166, v172
	v_pk_mul_f32 v[68:69], v[122:123], v[68:69]
	v_cndmask_b32_e64 v123, v131, v133, s[12:13]
	v_cndmask_b32_e64 v122, v130, v132, s[14:15]
	v_pk_mul_f32 v[122:123], v[94:95], v[122:123]
	v_rcp_f32_e32 v172, v174
	v_pk_mul_f32 v[124:125], v[122:123], v[164:165]
	v_cndmask_b32_e64 v123, v135, v137, s[16:17]
	v_cndmask_b32_e64 v122, v134, v136, s[18:19]
	v_pk_mul_f32 v[122:123], v[92:93], v[122:123]
	v_pk_mul_f32 v[168:169], v[168:169], v[178:179]
	v_pk_mul_f32 v[126:127], v[122:123], v[166:167]
	v_cndmask_b32_e64 v123, v139, v141, s[20:21]
	v_cndmask_b32_e64 v122, v138, v140, s[22:23]
	v_rcp_f32_e32 v174, v176
	v_pk_mul_f32 v[168:169], v[168:169], v[56:57] op_sel_hi:[1,0]
	v_pk_mul_f32 v[122:123], v[90:91], v[122:123]
	v_cvt_pk_bf16_f32 v71, v168, v169
	v_pk_mul_f32 v[128:129], v[122:123], v[172:173]
	v_cndmask_b32_e64 v123, v161, v163, s[24:25]
	v_cndmask_b32_e64 v122, v160, v162, s[26:27]
	v_mov_b32_e32 v70, v57
	v_pk_mul_f32 v[122:123], v[88:89], v[122:123]
	v_pk_mul_f32 v[64:65], v[64:65], v[70:71] op_sel:[1,0] op_sel_hi:[0,0]
	v_pk_mul_f32 v[130:131], v[122:123], v[174:175]
	v_cvt_pk_bf16_f32 v64, v64, v65
	v_add_u32_e32 v122, 0x8800, v150
	ds_write2_b32 v122, v71, v64 offset1:36
	v_pk_mul_f32 v[64:65], v[68:69], v[58:59] op_sel:[1,0] op_sel_hi:[0,0]
	v_cvt_pk_bf16_f32 v68, v64, v65
	v_mov_b32_e32 v64, v59
	v_pk_mul_f32 v[64:65], v[124:125], v[64:65] op_sel:[1,0] op_sel_hi:[0,0]
	v_cvt_pk_bf16_f32 v64, v64, v65
	ds_write2_b32 v122, v68, v64 offset0:72 offset1:108
	v_pk_mul_f32 v[64:65], v[126:127], v[60:61] op_sel:[1,0] op_sel_hi:[0,0]
	v_rcp_f32_e32 v176, v180
	v_cvt_pk_bf16_f32 v68, v64, v65
	v_mov_b32_e32 v64, v61
	v_pk_mul_f32 v[64:65], v[128:129], v[64:65] op_sel:[1,0] op_sel_hi:[0,0]
	v_cvt_pk_bf16_f32 v64, v64, v65
	ds_write2_b32 v122, v68, v64 offset0:144 offset1:180
	v_pk_mul_f32 v[64:65], v[130:131], v[62:63] op_sel:[1,0] op_sel_hi:[0,0]
	v_pk_mul_f32 v[66:67], v[66:67], v[176:177]
	v_cvt_pk_bf16_f32 v68, v64, v65
	v_mov_b32_e32 v64, v63
	v_pk_mul_f32 v[64:65], v[66:67], v[64:65] op_sel:[1,0] op_sel_hi:[0,0]
	v_cvt_pk_bf16_f32 v64, v64, v65
	ds_write2_b32 v122, v68, v64 offset0:216 offset1:252
	s_and_saveexec_b64 s[4:5], s[0:1]
	s_cbranch_execz .LBB0_286
	ds_write_b128 v145, v[56:59]
	ds_write_b128 v145, v[60:63] offset:16

.LBB0_451:
	s_lshl_b32 s6, s6, 5
	s_and_b32 s12, s6, 0x60
	s_mov_b64 s[6:7], 0x80
	v_readlane_b32 s14, v246, 48
	s_add_i32 m0, s19, 0x18000
	v_lshl_add_u64 v[6:7], v[6:7], 0, s[6:7]
	s_ashr_i32 s34, s14, 31
	s_lshl_b32 s9, s8, 13
	s_lshl_b32 s13, s12, 7
	global_load_lds_dwordx4 v[6:7], off
	v_lshl_add_u64 v[4:5], v[4:5], 0, s[6:7]
	s_add_i32 m0, s19, 0x1a000
	s_add_i32 s35, s19, 0x8000
	s_add_i32 s36, s19, 0xa000
	global_load_lds_dwordx4 v[4:5], off
	v_lshl_add_u64 v[0:1], v[0:1], 0, s[6:7]
	s_mov_b32 m0, s35
	s_add_u32 s10, s22, 0x40080
	global_load_lds_dwordx4 v[0:1], off
	v_lshl_add_u64 v[0:1], v[2:3], 0, s[6:7]
	s_mov_b32 m0, s36
	s_addc_u32 s11, s23, 0
	global_load_lds_dwordx4 v[0:1], off
	s_add_i32 m0, s19, 0x1c000
	v_lshl_add_u64 v[0:1], s[10:11], 0, v[130:131]
	global_load_lds_dwordx4 v[0:1], off
	v_lshl_add_u64 v[0:1], s[10:11], 0, v[134:135]
	s_add_i32 m0, s19, 0x1e000
	s_sext_i32_i16 s41, s0
	global_load_lds_dwordx4 v[0:1], off
	s_waitcnt vmcnt(8)
	s_barrier
	v_and_b32_e32 v0, 15, v171
	v_lshlrev_b32_e32 v1, 1, v11
	v_lshlrev_b32_e32 v2, 6, v171
	s_movk_i32 s0, 0x3c0
	v_lshlrev_b32_e32 v3, 2, v171
	v_and_or_b32 v2, v2, s0, v1
	v_and_b32_e32 v3, 32, v3
	v_lshl_or_b32 v145, s8, 6, v0
	v_lshl_or_b32 v0, v0, 6, v1
	v_lshlrev_b32_e32 v1, 8, v171
	v_bitop3_b32 v146, s13, v2, v3 bitop3:0xf6
	v_and_b32_e32 v1, 0x38000, v1
	v_lshlrev_b32_e32 v2, 11, v10
	v_or3_b32 v1, v8, v1, v2
	v_add_u32_e32 v136, v1, v9
	v_lshlrev_b32_e32 v1, 4, v12
	s_waitcnt vmcnt(6)
	s_cmpk_lt_u32 s1, 0x100
	v_and_b32_e32 v1, 0x78000, v1
	v_bitop3_b32 v0, v0, s9, v3 bitop3:0xde
	s_cselect_b64 s[8:9], -1, 0
	v_or3_b32 v1, v8, v1, v2
	s_add_i32 s38, 0, 0x10000
	s_add_i32 s39, 0, 0x14000
	s_mov_b32 s37, s14
	v_or_b32_e32 v147, s12, v11
	v_mov_b32_e32 v137, v131
	v_add_u32_e32 v138, v1, v9
	v_mov_b32_e32 v139, v131
	v_mov_b64_e32 v[140:141], 0x480
	v_mov_b64_e32 v[142:143], 0x47f
	v_add_u32_e32 v148, s38, v146
	v_add_u32_e32 v149, s39, v146
	v_add_u32_e32 v150, 0, v0
	s_movk_i32 s40, 0xc00
	v_mov_b32_e32 v151, 0x3e000000
	v_readlane_b32 s15, v246, 49
	s_barrier
	s_branch .LBB0_454

.LBB0_519:
	s_cmp_lt_i32 s78, 6
	s_cselect_b64 s[2:3], -1, 0
	s_add_u32 s34, s76, 0x100000
	s_addc_u32 s35, s77, 0
	s_add_u32 s30, s76, 0x6000000
	s_addc_u32 s31, s77, 0
	s_and_b64 s[36:37], s[2:3], s[0:1]
	s_andn2_b64 vcc, exec, s[36:37]
	s_cbranch_vccnz .LBB0_530
	s_cmpk_gt_i32 s54, 0x5ff
	s_cbranch_scc1 .LBB0_530
	v_lshrrev_b32_e32 v4, 4, v170
	v_mov_b32_e32 v1, 0
	v_and_b32_e32 v2, 48, v170
	v_mov_b32_e32 v3, v1
	v_lshlrev_b32_e32 v68, 2, v4
	v_and_b32_e32 v61, 15, v171
	v_lshlrev_b32_e32 v0, 3, v4
	v_lshl_add_u64 v[56:57], s[94:95], 0, v[2:3]
	v_or_b32_e32 v3, 0xffffffc0, v68
	v_sub_u32_e32 v3, v3, v61
	v_add_u32_e32 v4, 0, v0
	v_lshl_add_u64 v[58:59], s[94:95], 0, v[0:1]
	v_and_b32_e32 v0, 7, v171
	v_lshl_add_u32 v62, v0, 4, 0
	s_movk_i32 s0, 0x1930
	v_sub_u32_e32 v12, 0, v3
	s_movk_i32 s18, 0x41
	v_mad_u32_u24 v69, v0, s0, v62
	v_cmp_gt_u32_e64 s[0:1], s18, v12
	v_cvt_f32_u32_e32 v70, v12
	v_not_b32_e32 v12, v3
	v_cvt_f32_u32_e32 v71, v12
	v_sub_u32_e32 v12, -2, v3
	v_cvt_f32_u32_e32 v72, v12
	v_sub_u32_e32 v12, -3, v3
	v_cvt_f32_u32_e32 v73, v12
	v_sub_u32_e32 v12, -16, v3
	v_cvt_f32_u32_e32 v74, v12
	v_sub_u32_e32 v12, 0xffffffef, v3
	v_cvt_f32_u32_e32 v75, v12
	v_sub_u32_e32 v12, 0xffffffee, v3
	v_cvt_f32_u32_e32 v76, v12
	v_sub_u32_e32 v12, 0xffffffed, v3
	v_cvt_f32_u32_e32 v77, v12
	v_sub_u32_e32 v12, 0xffffffe0, v3
	v_cvt_f32_u32_e32 v78, v12
	v_sub_u32_e32 v12, 0xffffffdf, v3
	v_cvt_f32_u32_e32 v79, v12
	v_sub_u32_e32 v12, 0xffffffde, v3
	v_cvt_f32_u32_e32 v80, v12
	v_sub_u32_e32 v12, 0xffffffdd, v3
	v_cvt_f32_u32_e32 v81, v12
	v_sub_u32_e32 v12, 0xffffffd0, v3
	v_cvt_f32_u32_e32 v82, v12
	v_add_u32_e32 v12, 49, v3
	v_sub_u32_e32 v13, 0xffffffcf, v3
	v_max_i32_e32 v12, v12, v13
	v_cvt_f32_u32_e32 v83, v12
	v_add_u32_e32 v12, 50, v3
	v_sub_u32_e32 v13, 0xffffffce, v3
	v_max_i32_e32 v12, v12, v13
	v_cvt_f32_u32_e32 v84, v12
	v_add_u32_e32 v12, 51, v3
	v_sub_u32_e32 v13, 0xffffffcd, v3
	v_max_i32_e32 v12, v12, v13
	v_cvt_f32_u32_e32 v85, v12
	v_add_u32_e32 v12, 64, v3
	v_sub_u32_e32 v13, 0xffffffc0, v3
	v_max_i32_e32 v12, v12, v13
	v_cvt_f32_u32_e32 v86, v12
	v_add_u32_e32 v12, 0x41, v3
	v_sub_u32_e32 v13, 0xffffffbf, v3
	v_max_i32_e32 v12, v12, v13
	v_cvt_f32_u32_e32 v87, v12
	v_add_u32_e32 v12, 0x42, v3
	v_sub_u32_e32 v13, 0xffffffbe, v3
	v_max_i32_e32 v12, v12, v13
	v_cvt_f32_u32_e32 v88, v12
	v_add_u32_e32 v12, 0x43, v3
	v_sub_u32_e32 v13, 0xffffffbd, v3
	v_max_i32_e32 v12, v12, v13
	v_cvt_f32_u32_e32 v89, v12
	v_add_u32_e32 v12, 0x50, v3
	v_cvt_f32_u32_e32 v90, v12
	v_add_u32_e32 v12, 0x51, v3
	v_cvt_f32_u32_e32 v91, v12
	v_add_u32_e32 v12, 0x52, v3
	v_cvt_f32_u32_e32 v92, v12
	v_add_u32_e32 v12, 0x53, v3
	v_cvt_f32_u32_e32 v93, v12
	v_add_u32_e32 v12, 0x60, v3
	v_cvt_f32_u32_e32 v94, v12
	v_add_u32_e32 v12, 0x61, v3
	v_cvt_f32_u32_e32 v95, v12
	v_add_u32_e32 v12, 0x62, v3
	v_cvt_f32_u32_e32 v96, v12
	v_add_u32_e32 v12, 0x63, v3
	v_cvt_f32_u32_e32 v97, v12
	v_add_u32_e32 v12, 0x70, v3
	v_cvt_f32_u32_e32 v98, v12
	v_add_u32_e32 v12, 0x71, v3
	s_add_i32 s20, s55, 2
	s_add_i32 s21, s55, 4
	s_add_i32 s22, s55, 6
	s_add_i32 s23, s55, 8
	v_cvt_f32_u32_e32 v99, v12
	v_add_u32_e32 v12, 0x72, v3
	s_lshl_b32 s45, s20, 4
	s_lshl_b32 s47, s21, 4
	s_lshl_b32 s49, s22, 4
	s_lshl_b32 s51, s23, 4
	v_cmp_gt_u32_e64 s[8:9], s18, v12
	v_cvt_f32_u32_e32 v100, v12
	v_add_u32_e32 v12, 0x73, v3
	v_lshl_add_u32 v111, s20, 5, v4
	v_lshl_add_u32 v112, s21, 5, v4
	v_lshl_add_u32 v113, s22, 5, v4
	v_lshl_add_u32 v114, s23, 5, v4
	s_add_i32 s20, s55, 10
	s_add_i32 s21, s55, 12
	s_add_i32 s22, s55, 14
	s_add_i32 s23, s55, 16
	v_cmp_gt_u32_e64 s[10:11], s18, v12
	v_cvt_f32_u32_e32 v101, v12
	v_add_u32_e32 v12, 0x80, v3
	v_lshl_add_u32 v107, s55, 5, v4
	v_lshl_add_u32 v115, s20, 5, v4
	v_lshl_add_u32 v116, s21, 5, v4
	v_lshl_add_u32 v117, s22, 5, v4
	v_lshl_add_u32 v118, s23, 5, v4
	v_mbcnt_lo_u32_b32 v4, -1, 0
	s_movk_i32 s2, 0xffbe
	s_movk_i32 s4, 0xffbd
	s_movk_i32 s6, 0xffbc
	v_cmp_gt_u32_e64 s[12:13], s18, v12
	v_cvt_f32_u32_e32 v102, v12
	v_add_u32_e32 v12, 0x81, v3
	v_mbcnt_hi_u32_b32 v4, -1, v4
	v_cmp_lt_u32_e64 s[2:3], s2, v3
	v_cmp_lt_u32_e64 s[4:5], s4, v3
	v_cmp_lt_u32_e64 s[6:7], s6, v3
	v_cmp_gt_u32_e64 s[14:15], s18, v12
	v_cvt_f32_u32_e32 v103, v12
	v_add_u32_e32 v12, 0x82, v3
	v_add_u32_e32 v3, 0x83, v3
	v_and_b32_e32 v20, 64, v4
	v_cmp_gt_u32_e64 s[16:17], s18, v12
	v_cmp_gt_u32_e64 s[18:19], s18, v3
	v_cvt_f32_u32_e32 v105, v3
	s_movk_i32 s24, 0x328
	v_mov_b32_e32 v3, 0x3280
	v_xor_b32_e32 v19, 16, v4
	v_add_u32_e32 v20, 64, v20
	v_mad_u32_u24 v108, v61, s24, v3
	v_mov_b32_e32 v3, 0x6500
	s_lshl_b32 s53, s20, 4
	s_lshl_b32 s61, s21, 4
	v_cmp_lt_i32_e64 s[20:21], v19, v20
	s_lshl_b32 s42, s55, 4
	v_mad_u32_u24 v109, v61, s24, v3
	s_mov_b64 s[24:25], s[76:77]
	v_cndmask_b32_e64 v19, v4, v19, s[20:21]
	s_add_i32 s44, s42, 16
	s_add_i32 s46, s42, 48
	s_add_i32 s48, s42, 0x50
	s_add_i32 s50, s42, 0x70
	v_cvt_f32_u32_e32 v104, v12
	v_or_b32_e32 v3, 48, v170
	s_add_i32 s52, s42, 0x90
	s_add_i32 s60, s42, 0xb0
	s_add_i32 s74, s42, 0xd0
	s_lshl_b32 s75, s22, 4
	s_mov_b64 s[26:27], s[78:79]
	s_add_i32 s76, s42, 0xf0
	s_lshl_b32 s77, s23, 4
	v_lshlrev_b32_e32 v119, 2, v19
	v_xor_b32_e32 v19, 32, v4
	v_or_b32_e32 v63, s42, v61
	v_and_b32_e32 v2, 48, v171
	s_movk_i32 s43, 0x90
	v_or_b32_e32 v1, s44, v61
	v_or_b32_e32 v5, s45, v61
	v_or_b32_e32 v6, s46, v61
	v_or_b32_e32 v7, s47, v61
	v_or_b32_e32 v8, s48, v61
	v_or_b32_e32 v9, s49, v61
	v_or_b32_e32 v10, s50, v61
	v_or_b32_e32 v11, s51, v61
	v_mul_u32_u24_e32 v110, 0x328, v3
	v_or_b32_e32 v3, s52, v61
	v_or_b32_e32 v12, s53, v61
	v_or_b32_e32 v13, s60, v61
	v_or_b32_e32 v14, s61, v61
	v_or_b32_e32 v15, s74, v61
	v_or_b32_e32 v16, s75, v61
	v_or_b32_e32 v17, s76, v61
	v_or_b32_e32 v18, s77, v61
	v_cmp_lt_i32_e64 s[20:21], v19, v20
	v_add_u32_e32 v2, 0, v2
	v_lshlrev_b32_e32 v60, 3, v0
	v_mul_lo_u32 v0, v63, s43
	v_mul_lo_u32 v1, v1, s43
	v_mul_lo_u32 v5, v5, s43
	v_mul_lo_u32 v6, v6, s43
	v_mul_lo_u32 v7, v7, s43
	v_mul_lo_u32 v8, v8, s43
	v_mul_lo_u32 v9, v9, s43
	v_mul_lo_u32 v10, v10, s43
	v_mul_lo_u32 v11, v11, s43
	v_mul_lo_u32 v3, v3, s43
	v_mul_lo_u32 v12, v12, s43
	v_mul_lo_u32 v13, v13, s43
	v_mul_lo_u32 v14, v14, s43
	v_mul_lo_u32 v15, v15, s43
	v_mul_lo_u32 v16, v16, s43
	v_mul_lo_u32 v17, v17, s43
	v_mul_lo_u32 v18, v18, s43
	s_add_u32 s38, s24, 0x9000000
	s_mov_b64 s[66:67], s[26:27]
	v_cndmask_b32_e64 v4, v4, v19, s[20:21]
	v_cmp_gt_u32_e32 vcc, 16, v170
	v_mul_u32_u24_e32 v106, 0x328, v61
	s_mov_b64 s[64:65], s[24:25]
	s_addc_u32 s39, s25, 0
	v_lshlrev_b32_e32 v120, 2, v4
	v_add_u32_e32 v121, 0xfffffe00, v171
	v_lshrrev_b32_e32 v122, 2, v171
	s_movk_i32 s80, 0x600
	s_mov_b32 s81, 0xffff0000
	s_movk_i32 s82, 0xc00
	v_add_u32_e32 v123, v2, v0
	v_add_u32_e32 v124, v2, v1
	v_add_u32_e32 v125, v2, v5
	v_add_u32_e32 v126, v2, v6
	v_add_u32_e32 v127, v2, v7
	v_add_u32_e32 v128, v2, v8
	v_add_u32_e32 v129, v2, v9
	v_add_u32_e32 v130, v2, v10
	v_add_u32_e32 v131, v2, v11
	s_mov_b32 s83, 0xf149f2ca
	v_add_u32_e32 v132, v2, v3
	v_add_u32_e32 v133, v2, v12
	v_add_u32_e32 v134, v2, v13
	v_add_u32_e32 v135, v2, v14
	v_add_u32_e32 v136, v2, v15
	v_add_u32_e32 v137, v2, v16
	v_add_u32_e32 v138, v2, v17
	v_add_u32_e32 v139, v2, v18
	v_mov_b32_e32 v140, 0x42800000
	v_mov_b32_e32 v141, 0xf149f2ca
	v_add_u32_e32 v184, v107, v106
	v_add_u32_e32 v184, 0xe000, v184
	v_add_u32_e32 v185, v107, v108
	v_add_u32_e32 v185, 0xe000, v185
	v_add_u32_e32 v186, v107, v109
	v_add_u32_e32 v186, 0xe000, v186
	v_add_u32_e32 v187, v107, v110
	v_add_u32_e32 v187, 0xe000, v187
	v_add_u32_e32 v188, v111, v106
	v_add_u32_e32 v188, 0xe000, v188
	v_add_u32_e32 v189, v111, v108
	v_add_u32_e32 v189, 0xe000, v189
	v_add_u32_e32 v190, v111, v109
	v_add_u32_e32 v190, 0xe000, v190
	v_add_u32_e32 v191, v111, v110
	v_add_u32_e32 v191, 0xe000, v191
	v_add_u32_e32 v192, v112, v106
	v_add_u32_e32 v192, 0xe000, v192
	v_add_u32_e32 v193, v112, v108
	v_add_u32_e32 v193, 0xe000, v193
	v_add_u32_e32 v194, v112, v109
	v_add_u32_e32 v194, 0xe000, v194
	v_add_u32_e32 v195, v112, v110
	v_add_u32_e32 v195, 0xe000, v195
	v_add_u32_e32 v196, v113, v106
	v_add_u32_e32 v196, 0xe000, v196
	v_add_u32_e32 v197, v113, v108
	v_add_u32_e32 v197, 0xe000, v197
	v_add_u32_e32 v198, v113, v109
	v_add_u32_e32 v198, 0xe000, v198
	v_add_u32_e32 v199, v113, v110
	v_add_u32_e32 v199, 0xe000, v199
	v_add_u32_e32 v200, v114, v106
	v_add_u32_e32 v200, 0xe000, v200
	v_add_u32_e32 v201, v114, v108
	v_add_u32_e32 v201, 0xe000, v201
	v_add_u32_e32 v202, v114, v109
	v_add_u32_e32 v202, 0xe000, v202
	v_add_u32_e32 v203, v114, v110
	v_add_u32_e32 v203, 0xe000, v203
	v_add_u32_e32 v204, v115, v106
	v_add_u32_e32 v204, 0xe000, v204
	v_add_u32_e32 v205, v115, v108
	v_add_u32_e32 v205, 0xe000, v205
	v_add_u32_e32 v206, v115, v109
	v_add_u32_e32 v206, 0xe000, v206
	v_add_u32_e32 v207, v115, v110
	v_add_u32_e32 v207, 0xe000, v207
	v_add_u32_e32 v208, v116, v106
	v_add_u32_e32 v208, 0xe000, v208
	v_add_u32_e32 v209, v116, v108
	v_add_u32_e32 v209, 0xe000, v209
	v_add_u32_e32 v210, v116, v109
	v_add_u32_e32 v210, 0xe000, v210
	v_add_u32_e32 v211, v116, v110
	v_add_u32_e32 v211, 0xe000, v211
	v_add_u32_e32 v212, v117, v106
	v_add_u32_e32 v212, 0xe000, v212
	v_add_u32_e32 v213, v117, v108
	v_add_u32_e32 v213, 0xe000, v213
	v_add_u32_e32 v214, v117, v109
	v_add_u32_e32 v214, 0xe000, v214
	v_add_u32_e32 v215, v117, v110
	v_add_u32_e32 v215, 0xe000, v215
	v_add_u32_e32 v216, v118, v106
	v_add_u32_e32 v216, 0xe000, v216
	v_add_u32_e32 v217, v118, v108
	v_add_u32_e32 v217, 0xe000, v217
	v_add_u32_e32 v218, v118, v109
	v_add_u32_e32 v218, 0xe000, v218
	s_branch .LBB0_523

.LBB0_524:
	v_and_b32_e32 v20, 0x1fe, v2
	v_add_u32_e32 v4, s89, v20
	v_cmp_lt_i32_e64 s[20:21], -1, v4
	v_cmp_gt_i32_e64 s[22:23], s88, v4
	v_or_b32_e32 v6, 1, v4
	s_and_b64 s[22:23], s[20:21], s[22:23]
	v_cmp_gt_i32_e64 s[24:25], s88, v6
	v_cndmask_b32_e64 v4, 0, v4, s[22:23]
	s_and_b64 s[20:21], s[20:21], s[24:25]
	v_lshlrev_b32_e32 v4, s90, v4
	v_add_u32_e32 v4, s91, v4
	v_cndmask_b32_e64 v6, 0, v6, s[20:21]
	v_mad_i64_i32 v[4:5], s[24:25], v4, s80, v[0:1]
	v_lshlrev_b32_e32 v6, s90, v6
	v_add_u32_e32 v6, s91, v6
	v_lshlrev_b64 v[12:13], 1, v[4:5]
	v_mad_i64_i32 v[8:9], s[24:25], v6, s80, v[0:1]
	v_lshl_add_u64 v[4:5], s[30:31], 0, v[12:13]
	global_load_dwordx4 v[4:7], v[4:5], off nt
	v_lshlrev_b64 v[16:17], 1, v[8:9]
	v_lshl_add_u64 v[8:9], s[30:31], 0, v[16:17]
	v_lshl_add_u64 v[12:13], s[38:39], 0, v[12:13]
	v_lshl_add_u64 v[16:17], s[38:39], 0, v[16:17]
	global_load_dwordx4 v[8:11], v[8:9], off nt
	v_mad_u32_u24 v21, v20, s43, v62
	global_load_dwordx4 v[12:15], v[12:13], off nt
	v_add_u32_e32 v3, 0x200, v3
	global_load_dwordx4 v[16:19], v[16:17], off nt
	s_waitcnt vmcnt(3)
	v_cndmask_b32_e64 v7, 0, v7, s[22:23]
	v_cndmask_b32_e64 v6, 0, v6, s[22:23]
	v_cndmask_b32_e64 v5, 0, v5, s[22:23]
	v_cndmask_b32_e64 v4, 0, v4, s[22:23]
	ds_write_b128 v21, v[4:7]
	v_or_b32_e32 v4, 1, v2
	s_waitcnt vmcnt(2)
	v_cndmask_b32_e64 v11, 0, v11, s[20:21]
	s_waitcnt vmcnt(1)
	v_cndmask_b32_e64 v12, 0, v12, s[22:23]
	v_cndmask_b32_e64 v10, 0, v10, s[20:21]
	s_waitcnt vmcnt(0)
	v_cndmask_b32_e64 v19, 0, v19, s[20:21]
	v_cndmask_b32_e64 v18, 0, v18, s[20:21]
	v_cndmask_b32_e64 v17, 0, v17, s[20:21]
	v_cndmask_b32_e64 v16, 0, v16, s[20:21]
	v_cndmask_b32_e64 v9, 0, v9, s[20:21]
	v_cndmask_b32_e64 v8, 0, v8, s[20:21]
	v_mad_u64_u32 v[4:5], s[20:21], v4, s43, v[62:63]
	ds_write_b128 v4, v[8:11]
	v_lshl_add_u32 v4, v20, 1, v69
	v_and_b32_e32 v5, 0xffff, v12
	v_lshrrev_b32_e32 v6, 16, v12
	v_cndmask_b32_e64 v13, 0, v13, s[22:23]
	v_lshl_or_b32 v5, v16, 16, v5
	v_and_or_b32 v6, v16, s81, v6
	v_add_u32_e32 v7, 0xe100, v4
	ds_write2_b32 v7, v5, v6 offset1:202
	v_and_b32_e32 v5, 0xffff, v13
	v_lshrrev_b32_e32 v6, 16, v13
	v_cndmask_b32_e64 v14, 0, v14, s[22:23]
	v_lshl_or_b32 v5, v17, 16, v5
	v_and_or_b32 v6, v17, s81, v6
	v_add_u32_e32 v7, 0xe700, v4
	ds_write2_b32 v7, v5, v6 offset0:20 offset1:222
	v_and_b32_e32 v5, 0xffff, v14
	v_lshrrev_b32_e32 v6, 16, v14
	v_cndmask_b32_e64 v15, 0, v15, s[22:23]
	v_lshl_or_b32 v5, v18, 16, v5
	v_and_or_b32 v6, v18, s81, v6
	v_add_u32_e32 v7, 0xed00, v4
	s_movk_i32 s20, 0x43f
	ds_write2_b32 v7, v5, v6 offset0:40 offset1:242
	v_and_b32_e32 v5, 0xffff, v15
	v_lshrrev_b32_e32 v6, 16, v15
	v_cmp_lt_u32_e64 s[20:21], s20, v3
	v_lshl_or_b32 v5, v19, 16, v5
	v_and_or_b32 v6, v19, s81, v6
	v_add_u32_e32 v4, 0xf380, v4
	v_add_u32_e32 v2, 0x80, v2
	s_or_b64 s[40:41], s[20:21], s[40:41]
	ds_write2_b32 v4, v5, v6 offset0:28 offset1:230
	s_andn2_b64 exec, exec, s[40:41]
	s_cbranch_execnz .LBB0_524
	s_or_b64 exec, exec, s[40:41]
	v_add_u32_e32 v4, s27, v63
	s_lshl_b64 s[22:23], s[28:29], 1
	v_lshlrev_b32_e32 v2, s90, v4
	v_lshl_add_u64 v[0:1], v[56:57], 0, s[22:23]
	v_add_u32_e32 v2, s91, v2
	v_mad_i64_i32 v[2:3], s[20:21], v2, s82, v[0:1]
	global_load_dwordx4 v[12:15], v[2:3], off nt
	global_load_dwordx4 v[20:23], v[2:3], off offset:64 nt
	v_add_u32_e32 v2, 0x80, v4
	v_lshlrev_b32_e32 v2, s90, v2
	v_add_u32_e32 v2, s91, v2
	v_mad_i64_i32 v[0:1], s[20:21], v2, s82, v[0:1]
	s_lshl_b32 s20, s26, 3
	s_or_b32 s20, s33, s20
	s_add_i32 s20, s20, 1
	v_cvt_f32_i32_e32 v8, s20
	s_mov_b32 s20, 0xc2fc0000
	s_lshl_b32 s24, 1, s90
	v_or_b32_e32 v54, s27, v61
	v_mul_f32_e32 v9, 0xbeaaaaab, v8
	v_cmp_gt_f32_e64 s[20:21], s20, v9
	global_load_dwordx4 v[4:7], v[0:1], off nt
	s_nop 0
	global_load_dwordx4 v[0:3], v[0:1], off offset:64 nt
	v_cndmask_b32_e64 v9, 0, v140, s[20:21]
	v_fmac_f32_e32 v9, 0xbeaaaaab, v8
	v_exp_f32_e32 v8, v9
	v_cvt_f32_u32_e32 v9, s24
	s_and_b64 s[20:21], s[20:21], exec
	s_cselect_b32 s20, 0xffffffc0, 0
	v_ldexp_f32 v8, v8, s20
	v_mul_f32_e32 v55, v8, v9
	v_add_u32_e32 v8, s42, v54
	v_lshlrev_b32_e32 v8, s90, v8
	s_waitcnt lgkmcnt(0)
	s_barrier
	v_add_u32_e32 v52, s91, v8
	ds_read_b128 v[8:11], v123
	ds_read_b128 v[16:19], v123 offset:64
	s_ashr_i32 s27, s26, 31
	s_lshl_b64 s[20:21], s[26:27], 19
	s_add_u32 s20, s34, s20
	v_lshl_add_u64 v[64:65], v[58:59], 0, s[22:23]
	s_addc_u32 s21, s35, s21
	s_lshl_b32 s22, s33, 2
	s_add_u32 s40, s20, s22
	s_addc_u32 s41, s21, 0
	s_add_i32 s20, s89, s42
	s_cmp_gt_i32 s20, -1
	s_cselect_b64 s[22:23], -1, 0
	v_or_b32_e32 v53, s20, v68
	s_and_b64 s[24:25], s[0:1], s[22:23]
	v_cmp_gt_i32_e64 s[20:21], s88, v53
	s_and_b64 s[20:21], s[24:25], s[20:21]
	v_or_b32_e32 v67, 1, v53
	s_and_b64 s[24:25], s[2:3], s[22:23]
	s_waitcnt vmcnt(3) lgkmcnt(1)
	v_mfma_f32_16x16x32_bf16 v[8:11], v[8:11], v[12:15], 0
	s_waitcnt vmcnt(2) lgkmcnt(0)
	v_mfma_f32_16x16x32_bf16 v[48:51], v[16:19], v[20:23], v[8:11]
	ds_read_b128 v[16:19], v124 offset:64
	s_nop 4
	ds_read_b128 v[8:11], v124
	s_waitcnt lgkmcnt(0)
	v_mfma_f32_16x16x32_bf16 v[8:11], v[8:11], v[12:15], 0
	v_fma_f32 v48, -v55, v70, v48
	v_cndmask_b32_e64 v48, v141, v48, s[20:21]
	v_cmp_gt_i32_e64 s[20:21], s88, v67
	v_mfma_f32_16x16x32_bf16 v[44:47], v[16:19], v[20:23], v[8:11]
	ds_read_b128 v[16:19], v125 offset:64
	s_and_b64 s[20:21], s[24:25], s[20:21]
	v_fma_f32 v49, -v55, v71, v49
	s_nop 0
	ds_read_b128 v[8:11], v125
	s_waitcnt lgkmcnt(0)
	v_mfma_f32_16x16x32_bf16 v[8:11], v[8:11], v[12:15], 0
	v_or_b32_e32 v67, 2, v53
	v_cndmask_b32_e64 v49, v141, v49, s[20:21]
	s_and_b64 s[24:25], s[4:5], s[22:23]
	v_mfma_f32_16x16x32_bf16 v[40:43], v[16:19], v[20:23], v[8:11]
	ds_read_b128 v[16:19], v126 offset:64
	v_cmp_gt_i32_e64 s[20:21], s88, v67
	s_and_b64 s[20:21], s[24:25], s[20:21]
	s_nop 0
	ds_read_b128 v[8:11], v126
	s_waitcnt lgkmcnt(0)
	v_mfma_f32_16x16x32_bf16 v[8:11], v[8:11], v[12:15], 0
	v_fma_f32 v50, -v55, v72, v50
	v_or_b32_e32 v53, 3, v53
	v_cndmask_b32_e64 v50, v141, v50, s[20:21]
	v_mfma_f32_16x16x32_bf16 v[36:39], v[16:19], v[20:23], v[8:11]
	ds_read_b128 v[16:19], v127 offset:64
	s_and_b64 s[22:23], s[6:7], s[22:23]
	v_cmp_gt_i32_e64 s[20:21], s88, v53
	s_nop 0
	ds_read_b128 v[8:11], v127
	s_waitcnt lgkmcnt(0)
	v_mfma_f32_16x16x32_bf16 v[8:11], v[8:11], v[12:15], 0
	s_and_b64 s[20:21], s[22:23], s[20:21]
	v_fma_f32 v51, -v55, v73, v51
	v_cndmask_b32_e64 v51, v141, v51, s[20:21]
	v_mfma_f32_16x16x32_bf16 v[32:35], v[16:19], v[20:23], v[8:11]
	s_add_i32 s20, s89, s44
	s_cmp_gt_i32 s20, -1
	v_or_b32_e32 v53, s20, v68
	s_nop 0
	ds_read_b128 v[8:11], v128
	ds_read_b128 v[16:19], v128 offset:64
	s_cselect_b64 s[22:23], -1, 0
	v_cmp_gt_i32_e64 s[20:21], s88, v53
	s_and_b64 s[20:21], s[22:23], s[20:21]
	v_fma_f32 v44, -v55, v74, v44
	v_or_b32_e32 v67, 1, v53
	v_cndmask_b32_e64 v44, v141, v44, s[20:21]
	v_cmp_gt_i32_e64 s[20:21], s88, v67
	s_and_b64 s[20:21], s[22:23], s[20:21]
	v_fma_f32 v45, -v55, v75, v45
	v_or_b32_e32 v67, 2, v53
	v_cndmask_b32_e64 v45, v141, v45, s[20:21]
	v_cmp_gt_i32_e64 s[20:21], s88, v67
	s_and_b64 s[20:21], s[22:23], s[20:21]
	v_fma_f32 v46, -v55, v76, v46
	v_or_b32_e32 v53, 3, v53
	v_cndmask_b32_e64 v46, v141, v46, s[20:21]
	v_cmp_gt_i32_e64 s[20:21], s88, v53
	s_waitcnt lgkmcnt(1)
	v_mfma_f32_16x16x32_bf16 v[8:11], v[8:11], v[12:15], 0
	s_and_b64 s[20:21], s[22:23], s[20:21]
	v_fma_f32 v47, -v55, v77, v47
	v_cndmask_b32_e64 v47, v141, v47, s[20:21]
	s_add_i32 s20, s89, s45
	s_cmp_gt_i32 s20, -1
	v_or_b32_e32 v53, s20, v68
	s_cselect_b64 s[22:23], -1, 0
	v_cmp_gt_i32_e64 s[20:21], s88, v53
	s_waitcnt lgkmcnt(0)
	v_mfma_f32_16x16x32_bf16 v[28:31], v[16:19], v[20:23], v[8:11]
	s_and_b64 s[20:21], s[22:23], s[20:21]
	v_fma_f32 v40, -v55, v78, v40
	v_or_b32_e32 v67, 1, v53
	ds_read_b128 v[8:11], v129
	ds_read_b128 v[16:19], v129 offset:64
	v_cndmask_b32_e64 v40, v141, v40, s[20:21]
	v_cmp_gt_i32_e64 s[20:21], s88, v67
	s_and_b64 s[20:21], s[22:23], s[20:21]
	v_fma_f32 v41, -v55, v79, v41
	v_or_b32_e32 v67, 2, v53
	v_cndmask_b32_e64 v41, v141, v41, s[20:21]
	v_cmp_gt_i32_e64 s[20:21], s88, v67
	s_and_b64 s[20:21], s[22:23], s[20:21]
	v_fma_f32 v42, -v55, v80, v42
	v_or_b32_e32 v53, 3, v53
	v_cndmask_b32_e64 v42, v141, v42, s[20:21]
	v_cmp_gt_i32_e64 s[20:21], s88, v53
	s_and_b64 s[20:21], s[22:23], s[20:21]
	v_fma_f32 v43, -v55, v81, v43
	v_cndmask_b32_e64 v43, v141, v43, s[20:21]
	s_add_i32 s20, s89, s46
	s_cmp_gt_i32 s20, -1
	v_or_b32_e32 v53, s20, v68
	s_waitcnt lgkmcnt(1)
	v_mfma_f32_16x16x32_bf16 v[8:11], v[8:11], v[12:15], 0
	s_cselect_b64 s[22:23], -1, 0
	v_cmp_gt_i32_e64 s[20:21], s88, v53
	s_and_b64 s[20:21], s[22:23], s[20:21]
	v_fma_f32 v36, -v55, v82, v36
	v_or_b32_e32 v67, 1, v53
	v_cndmask_b32_e64 v36, v141, v36, s[20:21]
	v_cmp_gt_i32_e64 s[20:21], s88, v67
	s_and_b64 s[20:21], s[22:23], s[20:21]
	v_fma_f32 v37, -v55, v83, v37
	v_or_b32_e32 v67, 2, v53
	s_waitcnt lgkmcnt(0)
	v_mfma_f32_16x16x32_bf16 v[24:27], v[16:19], v[20:23], v[8:11]
	v_max_f32_e32 v66, 0xf149f2ca, v48
	v_cndmask_b32_e64 v37, v141, v37, s[20:21]
	v_cmp_gt_i32_e64 s[20:21], s88, v67
	ds_read_b128 v[8:11], v130
	ds_read_b128 v[16:19], v130 offset:64
	v_max3_f32 v66, v66, v49, v50
	s_and_b64 s[20:21], s[22:23], s[20:21]
	v_fma_f32 v38, -v55, v84, v38
	v_or_b32_e32 v53, 3, v53
	v_max3_f32 v66, v66, v51, v44
	v_cndmask_b32_e64 v38, v141, v38, s[20:21]
	v_cmp_gt_i32_e64 s[20:21], s88, v53
	v_max3_f32 v66, v66, v45, v46
	s_and_b64 s[20:21], s[22:23], s[20:21]
	v_fma_f32 v39, -v55, v85, v39
	v_max3_f32 v66, v66, v47, v40
	v_cndmask_b32_e64 v39, v141, v39, s[20:21]
	s_add_i32 s20, s89, s47
	v_max3_f32 v66, v66, v41, v42
	v_or_b32_e32 v53, s20, v68
	v_max3_f32 v66, v66, v43, v36
	v_cmp_gt_i32_e64 s[20:21], s88, v53
	v_fma_f32 v32, -v55, v86, v32
	v_max3_f32 v66, v66, v37, v38
	v_cndmask_b32_e64 v67, v141, v32, s[20:21]
	v_max3_f32 v32, v66, v39, v67
	v_or_b32_e32 v66, 1, v53
	s_waitcnt lgkmcnt(1)
	v_mfma_f32_16x16x32_bf16 v[8:11], v[8:11], v[12:15], 0
	v_cmp_gt_i32_e64 s[20:21], s88, v66
	v_fma_f32 v33, -v55, v87, v33
	v_or_b32_e32 v66, 2, v53
	v_cndmask_b32_e64 v33, v141, v33, s[20:21]
	v_cmp_gt_i32_e64 s[20:21], s88, v66
	v_fma_f32 v34, -v55, v88, v34
	v_or_b32_e32 v53, 3, v53
	v_cndmask_b32_e64 v34, v141, v34, s[20:21]
	v_cmp_gt_i32_e64 s[20:21], s88, v53
	v_fma_f32 v35, -v55, v89, v35
	s_waitcnt lgkmcnt(0)
	v_mfma_f32_16x16x32_bf16 v[16:19], v[16:19], v[20:23], v[8:11]
	v_cndmask_b32_e64 v35, v141, v35, s[20:21]
	s_add_i32 s20, s89, s48
	v_or_b32_e32 v53, s20, v68
	ds_read_b128 v[8:11], v131
	v_cmp_gt_i32_e64 s[20:21], s88, v53
	v_fma_f32 v28, -v55, v90, v28
	v_or_b32_e32 v66, 1, v53
	v_cndmask_b32_e64 v28, v141, v28, s[20:21]
	v_cmp_gt_i32_e64 s[20:21], s88, v66
	v_fma_f32 v29, -v55, v91, v29
	v_or_b32_e32 v66, 2, v53
	v_cndmask_b32_e64 v29, v141, v29, s[20:21]
	v_cmp_gt_i32_e64 s[20:21], s88, v66
	v_fma_f32 v30, -v55, v92, v30
	v_or_b32_e32 v53, 3, v53
	v_cndmask_b32_e64 v30, v141, v30, s[20:21]
	v_cmp_gt_i32_e64 s[20:21], s88, v53
	v_fma_f32 v31, -v55, v93, v31
	v_fma_f32 v24, -v55, v94, v24
	v_cndmask_b32_e64 v31, v141, v31, s[20:21]
	s_add_i32 s20, s89, s49
	v_or_b32_e32 v53, s20, v68
	v_cmp_gt_i32_e64 s[20:21], s88, v53
	v_or_b32_e32 v66, 1, v53
	v_fma_f32 v25, -v55, v95, v25
	v_cndmask_b32_e64 v24, v141, v24, s[20:21]
	v_cmp_gt_i32_e64 s[20:21], s88, v66
	v_or_b32_e32 v66, 2, v53
	s_waitcnt lgkmcnt(0)
	v_mfma_f32_16x16x32_bf16 v[142:145], v[8:11], v[12:15], 0
	ds_read_b128 v[12:15], v131 offset:64
	v_cndmask_b32_e64 v25, v141, v25, s[20:21]
	v_cmp_gt_i32_e64 s[20:21], s88, v66
	v_fma_f32 v26, -v55, v96, v26
	v_or_b32_e32 v53, 3, v53
	v_cndmask_b32_e64 v26, v141, v26, s[20:21]
	v_cmp_gt_i32_e64 s[20:21], s88, v53
	v_fma_f32 v27, -v55, v97, v27
	v_fma_f32 v16, -v55, v98, v16
	v_cndmask_b32_e64 v27, v141, v27, s[20:21]
	s_add_i32 s20, s89, s50
	v_or_b32_e32 v53, s20, v68
	v_cmp_gt_i32_e64 s[20:21], s88, v53
	v_or_b32_e32 v66, 1, v53
	v_fma_f32 v17, -v55, v99, v17
	v_cndmask_b32_e64 v16, v141, v16, s[20:21]
	v_cmp_gt_i32_e64 s[20:21], s88, v66
	v_or_b32_e32 v66, 2, v53
	v_fma_f32 v18, -v55, v100, v18
	v_cndmask_b32_e64 v17, v141, v17, s[20:21]
	v_cmp_gt_i32_e64 s[20:21], s88, v66
	s_and_b64 s[20:21], s[8:9], s[20:21]
	v_or_b32_e32 v53, 3, v53
	v_cndmask_b32_e64 v18, v141, v18, s[20:21]
	v_cmp_gt_i32_e64 s[20:21], s88, v53
	s_waitcnt lgkmcnt(0)
	v_mfma_f32_16x16x32_bf16 v[20:23], v[12:15], v[20:23], v[142:145]
	s_and_b64 s[20:21], s[10:11], s[20:21]
	v_fma_f32 v19, -v55, v101, v19
	v_cndmask_b32_e64 v19, v141, v19, s[20:21]
	s_add_i32 s20, s89, s51
	v_or_b32_e32 v53, s20, v68
	v_cmp_gt_i32_e64 s[26:27], s88, v53
	v_max3_f32 v32, v32, v33, v34
	s_and_b64 s[20:21], s[12:13], s[26:27]
	v_fma_f32 v20, -v55, v102, v20
	v_or_b32_e32 v66, 1, v53
	v_max3_f32 v32, v32, v35, v28
	v_cndmask_b32_e64 v20, v141, v20, s[20:21]
	v_cmp_gt_i32_e64 s[20:21], s88, v66
	v_max3_f32 v32, v32, v29, v30
	s_and_b64 s[22:23], s[14:15], s[20:21]
	v_fma_f32 v21, -v55, v103, v21
	v_max3_f32 v32, v32, v31, v24
	v_cndmask_b32_e64 v66, v141, v21, s[22:23]
	v_or_b32_e32 v21, 2, v53
	v_max3_f32 v32, v32, v25, v26
	v_cmp_gt_i32_e64 s[22:23], s88, v21
	v_max3_f32 v32, v32, v27, v16
	s_and_b64 s[24:25], s[16:17], s[22:23]
	v_fma_f32 v21, -v55, v104, v22
	v_or_b32_e32 v22, 3, v53
	v_max3_f32 v32, v32, v17, v18
	v_cndmask_b32_e64 v142, v141, v21, s[24:25]
	v_cmp_gt_i32_e64 s[24:25], s88, v22
	v_max3_f32 v32, v32, v19, v20
	s_and_b64 s[28:29], s[18:19], s[24:25]
	v_fma_f32 v22, -v55, v105, v23
	v_max3_f32 v21, v32, v66, v142
	v_cndmask_b32_e64 v23, v141, v22, s[28:29]
	v_max3_f32 v21, v21, v23, s83
	ds_bpermute_b32 v22, v119, v21
	s_waitcnt lgkmcnt(0)
	v_max_f32_e32 v22, v22, v22
	v_max_f32_e32 v21, v21, v22
	ds_bpermute_b32 v22, v120, v21
	s_waitcnt lgkmcnt(0)
	v_max_f32_e32 v22, v22, v22
	v_max_f32_e32 v32, v21, v22
	v_sub_f32_e32 v22, v49, v32
	v_mul_f32_e32 v22, 0x3fb8aa3b, v22
	v_exp_f32_e32 v49, v22
	v_sub_f32_e32 v22, v50, v32
	v_mul_f32_e32 v22, 0x3fb8aa3b, v22
	v_exp_f32_e32 v50, v22
	v_sub_f32_e32 v22, v51, v32
	v_mul_f32_e32 v22, 0x3fb8aa3b, v22
	v_exp_f32_e32 v51, v22
	v_sub_f32_e32 v22, v44, v32
	v_mul_f32_e32 v22, 0x3fb8aa3b, v22
	v_exp_f32_e32 v44, v22
	v_sub_f32_e32 v22, v45, v32
	v_mul_f32_e32 v22, 0x3fb8aa3b, v22
	v_exp_f32_e32 v45, v22
	v_sub_f32_e32 v22, v46, v32
	v_mul_f32_e32 v22, 0x3fb8aa3b, v22
	v_exp_f32_e32 v46, v22
	v_sub_f32_e32 v22, v47, v32
	v_mul_f32_e32 v22, 0x3fb8aa3b, v22
	v_exp_f32_e32 v47, v22
	v_sub_f32_e32 v22, v40, v32
	v_mul_f32_e32 v22, 0x3fb8aa3b, v22
	v_exp_f32_e32 v53, v22
	v_sub_f32_e32 v22, v41, v32
	v_mul_f32_e32 v22, 0x3fb8aa3b, v22
	v_exp_f32_e32 v143, v22
	v_sub_f32_e32 v22, v42, v32
	v_mul_f32_e32 v22, 0x3fb8aa3b, v22
	v_exp_f32_e32 v144, v22
	v_sub_f32_e32 v22, v43, v32
	v_sub_f32_e32 v21, v48, v32
	v_mul_f32_e32 v22, 0x3fb8aa3b, v22
	v_mul_f32_e32 v21, 0x3fb8aa3b, v21
	v_exp_f32_e32 v145, v22
	v_sub_f32_e32 v22, v36, v32
	v_exp_f32_e32 v48, v21
	v_mul_f32_e32 v22, 0x3fb8aa3b, v22
	v_exp_f32_e32 v146, v22
	v_sub_f32_e32 v22, v37, v32
	v_mul_f32_e32 v22, 0x3fb8aa3b, v22
	v_exp_f32_e32 v147, v22
	v_sub_f32_e32 v22, v38, v32
	v_add_f32_e32 v21, 0, v48
	v_mul_f32_e32 v22, 0x3fb8aa3b, v22
	v_add_f32_e32 v21, v49, v21
	v_exp_f32_e32 v148, v22
	v_sub_f32_e32 v22, v39, v32
	v_add_f32_e32 v21, v50, v21
	v_mul_f32_e32 v22, 0x3fb8aa3b, v22
	v_add_f32_e32 v21, v51, v21
	v_exp_f32_e32 v149, v22
	v_sub_f32_e32 v22, v67, v32
	v_add_f32_e32 v21, v44, v21
	v_mul_f32_e32 v22, 0x3fb8aa3b, v22
	v_add_f32_e32 v21, v45, v21
	v_exp_f32_e32 v67, v22
	v_sub_f32_e32 v22, v33, v32
	v_add_f32_e32 v21, v46, v21
	v_mul_f32_e32 v22, 0x3fb8aa3b, v22
	v_add_f32_e32 v21, v47, v21
	v_exp_f32_e32 v150, v22
	v_sub_f32_e32 v22, v34, v32
	v_add_f32_e32 v21, v53, v21
	v_mul_f32_e32 v22, 0x3fb8aa3b, v22
	v_add_f32_e32 v21, v143, v21
	v_exp_f32_e32 v151, v22
	v_sub_f32_e32 v22, v35, v32
	v_add_f32_e32 v21, v144, v21
	v_mul_f32_e32 v22, 0x3fb8aa3b, v22
	v_add_f32_e32 v21, v145, v21
	v_exp_f32_e32 v35, v22
	v_sub_f32_e32 v22, v28, v32
	v_add_f32_e32 v21, v146, v21
	v_mul_f32_e32 v22, 0x3fb8aa3b, v22
	v_add_f32_e32 v21, v147, v21
	v_exp_f32_e32 v152, v22
	v_sub_f32_e32 v22, v29, v32
	v_add_f32_e32 v21, v148, v21
	v_mul_f32_e32 v22, 0x3fb8aa3b, v22
	v_add_f32_e32 v21, v149, v21
	v_exp_f32_e32 v153, v22
	v_sub_f32_e32 v22, v30, v32
	v_add_f32_e32 v21, v67, v21
	v_mul_f32_e32 v22, 0x3fb8aa3b, v22
	v_add_f32_e32 v21, v150, v21
	v_exp_f32_e32 v154, v22
	v_sub_f32_e32 v22, v31, v32
	v_add_f32_e32 v21, v151, v21
	v_mul_f32_e32 v22, 0x3fb8aa3b, v22
	v_add_f32_e32 v21, v35, v21
	v_exp_f32_e32 v155, v22
	v_add_f32_e32 v21, v152, v21
	v_add_f32_e32 v21, v153, v21
	v_add_f32_e32 v21, v154, v21
	v_add_f32_e32 v22, v155, v21
	v_sub_f32_e32 v21, v24, v32
	v_mul_f32_e32 v21, 0x3fb8aa3b, v21
	v_exp_f32_e32 v21, v21
	v_sub_f32_e32 v17, v17, v32
	v_sub_f32_e32 v16, v16, v32
	v_mul_f32_e32 v17, 0x3fb8aa3b, v17
	v_add_f32_e32 v24, v21, v22
	v_sub_f32_e32 v22, v25, v32
	v_sub_f32_e32 v25, v26, v32
	v_mul_f32_e32 v22, 0x3fb8aa3b, v22
	v_mul_f32_e32 v25, 0x3fb8aa3b, v25
	v_exp_f32_e32 v22, v22
	v_exp_f32_e32 v156, v25
	v_sub_f32_e32 v25, v27, v32
	v_mul_f32_e32 v25, 0x3fb8aa3b, v25
	v_exp_f32_e32 v157, v25
	v_mul_f32_e32 v16, 0x3fb8aa3b, v16
	v_exp_f32_e32 v159, v17
	v_sub_f32_e32 v17, v18, v32
	v_exp_f32_e32 v158, v16
	v_mul_f32_e32 v17, 0x3fb8aa3b, v17
	v_add_f32_e32 v24, v22, v24
	v_exp_f32_e32 v160, v17
	v_sub_f32_e32 v17, v19, v32
	v_add_f32_e32 v24, v156, v24
	v_mul_f32_e32 v17, 0x3fb8aa3b, v17
	v_add_f32_e32 v24, v157, v24
	v_exp_f32_e32 v161, v17
	v_add_f32_e32 v16, v158, v24
	v_add_f32_e32 v16, v159, v16
	v_add_f32_e32 v16, v160, v16
	v_add_f32_e32 v17, v161, v16
	v_sub_f32_e32 v16, v20, v32
	v_mul_f32_e32 v16, 0x3fb8aa3b, v16
	v_exp_f32_e32 v16, v16
	v_cvt_pk_bf16_f32 v26, v44, v45
	v_cvt_pk_bf16_f32 v27, v46, v47
	v_cvt_pk_bf16_f32 v25, v50, v51
	v_add_f32_e32 v18, v16, v17
	v_sub_f32_e32 v17, v66, v32
	v_mul_f32_e32 v17, 0x3fb8aa3b, v17
	v_exp_f32_e32 v17, v17
	s_nop 0
	v_add_f32_e32 v19, v17, v18
	v_sub_f32_e32 v18, v142, v32
	v_mul_f32_e32 v18, 0x3fb8aa3b, v18
	v_exp_f32_e32 v18, v18
	s_nop 0
	v_add_f32_e32 v20, v18, v19
	v_sub_f32_e32 v19, v23, v32
	v_mul_f32_e32 v19, 0x3fb8aa3b, v19
	v_exp_f32_e32 v19, v19
	s_nop 0
	v_add_f32_e32 v23, v19, v20
	v_sub_f32_e32 v20, 0xf149f2ca, v32
	v_mul_f32_e32 v20, 0x3fb8aa3b, v20
	v_exp_f32_e32 v20, v20
	s_nop 0
	v_add_f32_e32 v23, v20, v23
	v_add_f32_e32 v23, v20, v23
	v_add_f32_e32 v23, v20, v23
	v_add_f32_e32 v23, v20, v23
	ds_bpermute_b32 v24, v119, v23
	s_waitcnt lgkmcnt(0)
	v_add_f32_e32 v33, v23, v24
	ds_read2_b64 v[28:31], v184 offset0:32 offset1:36
	ds_read2_b64 v[36:39], v185 offset0:32 offset1:36
	ds_read2_b64 v[40:43], v186 offset0:32 offset1:36
	ds_read2_b64 v[44:47], v187 offset0:32 offset1:36
	v_cvt_pk_bf16_f32 v24, v48, v49
	ds_read2_b64 v[48:51], v188 offset0:32 offset1:36
	s_waitcnt lgkmcnt(4)
	v_mfma_f32_16x16x32_bf16 v[28:31], v[28:31], v[24:27], 0
	ds_bpermute_b32 v34, v120, v33
	s_waitcnt lgkmcnt(0)
	v_add_f32_e32 v33, v33, v34
	v_mfma_f32_16x16x32_bf16 v[36:39], v[36:39], v[24:27], 0
	v_rcp_f32_e32 v34, v33
	v_mfma_f32_16x16x32_bf16 v[40:43], v[40:43], v[24:27], 0
	v_mfma_f32_16x16x32_bf16 v[24:27], v[44:47], v[24:27], 0
	v_cvt_pk_bf16_f32 v44, v53, v143
	v_cvt_pk_bf16_f32 v45, v144, v145
	v_cvt_pk_bf16_f32 v46, v146, v147
	v_cvt_pk_bf16_f32 v47, v148, v149
	s_nop 1
	v_mfma_f32_16x16x32_bf16 v[28:31], v[48:51], v[44:47], v[28:31]
	ds_read2_b64 v[48:51], v189 offset0:32 offset1:36
	s_waitcnt lgkmcnt(0)
	v_mfma_f32_16x16x32_bf16 v[36:39], v[48:51], v[44:47], v[36:39]
	ds_read2_b64 v[48:51], v190 offset0:32 offset1:36
	s_waitcnt lgkmcnt(0)
	v_mfma_f32_16x16x32_bf16 v[40:43], v[48:51], v[44:47], v[40:43]
	ds_read2_b64 v[48:51], v191 offset0:32 offset1:36
	s_waitcnt lgkmcnt(0)
	v_mfma_f32_16x16x32_bf16 v[24:27], v[48:51], v[44:47], v[24:27]
	ds_read2_b64 v[48:51], v192 offset0:32 offset1:36
	v_cvt_pk_bf16_f32 v44, v67, v150
	v_cvt_pk_bf16_f32 v45, v151, v35
	v_cvt_pk_bf16_f32 v46, v152, v153
	v_cvt_pk_bf16_f32 v47, v154, v155
	s_waitcnt lgkmcnt(0)
	s_nop 0
	v_mfma_f32_16x16x32_bf16 v[28:31], v[48:51], v[44:47], v[28:31]
	ds_read2_b64 v[48:51], v193 offset0:32 offset1:36
	s_waitcnt lgkmcnt(0)
	v_mfma_f32_16x16x32_bf16 v[36:39], v[48:51], v[44:47], v[36:39]
	ds_read2_b64 v[48:51], v194 offset0:32 offset1:36
	s_waitcnt lgkmcnt(0)
	v_mfma_f32_16x16x32_bf16 v[40:43], v[48:51], v[44:47], v[40:43]
	ds_read2_b64 v[48:51], v195 offset0:32 offset1:36
	s_waitcnt lgkmcnt(0)
	v_mfma_f32_16x16x32_bf16 v[24:27], v[48:51], v[44:47], v[24:27]
	v_cvt_pk_bf16_f32 v44, v21, v22
	ds_read2_b64 v[48:51], v196 offset0:32 offset1:36
	v_cvt_pk_bf16_f32 v45, v156, v157
	v_cvt_pk_bf16_f32 v46, v158, v159
	v_cvt_pk_bf16_f32 v47, v160, v161
	s_waitcnt lgkmcnt(0)
	s_nop 0
	v_mfma_f32_16x16x32_bf16 v[28:31], v[48:51], v[44:47], v[28:31]
	ds_read2_b64 v[48:51], v197 offset0:32 offset1:36
	s_waitcnt lgkmcnt(0)
	v_mfma_f32_16x16x32_bf16 v[36:39], v[48:51], v[44:47], v[36:39]
	ds_read2_b64 v[48:51], v198 offset0:32 offset1:36
	s_waitcnt lgkmcnt(0)
	v_mfma_f32_16x16x32_bf16 v[40:43], v[48:51], v[44:47], v[40:43]
	ds_read2_b64 v[48:51], v199 offset0:32 offset1:36
	s_waitcnt lgkmcnt(0)
	v_mfma_f32_16x16x32_bf16 v[44:47], v[48:51], v[44:47], v[24:27]
	v_cvt_pk_bf16_f32 v48, v16, v17
	v_cvt_pk_bf16_f32 v49, v18, v19
	ds_read2_b64 v[16:19], v200 offset0:32 offset1:36
	v_cvt_pk_bf16_f32 v50, v20, v20
	ds_read2_b64 v[20:23], v201 offset0:32 offset1:36
	v_mov_b32_e32 v51, v50
	ds_read2_b64 v[24:27], v202 offset0:32 offset1:36
	s_waitcnt lgkmcnt(2)
	v_mfma_f32_16x16x32_bf16 v[142:145], v[16:19], v[48:51], v[28:31]
	s_nop 2
	ds_read2_b64 v[28:31], v203 offset0:32 offset1:36
	s_waitcnt lgkmcnt(2)
	v_mfma_f32_16x16x32_bf16 v[36:39], v[20:23], v[48:51], v[36:39]
	s_nop 1
	v_mul_f32_e64 v66, v34, v144
	v_mul_f32_e64 v67, v34, v145
	s_waitcnt lgkmcnt(1)
	v_mfma_f32_16x16x32_bf16 v[40:43], v[24:27], v[48:51], v[40:43]
	s_waitcnt lgkmcnt(0)
	v_mfma_f32_16x16x32_bf16 v[44:47], v[28:31], v[48:51], v[44:47]
	s_nop 1
	v_mul_f32_e64 v36, v34, v36
	v_mul_f32_e64 v37, v34, v37
	v_pk_mul_f32 v[38:39], v[34:35], v[38:39] op_sel_hi:[0,1]
	v_mad_i64_i32 v[48:49], s[28:29], v52, s82, v[64:65]
	v_cvt_pk_bf16_f32 v36, v36, v37
	v_cvt_pk_bf16_f32 v37, v38, v39
	global_store_dwordx2 v[48:49], v[36:37], off offset:32
	v_pk_mul_f32 v[36:37], v[34:35], v[40:41] op_sel_hi:[0,1]
	v_pk_mul_f32 v[38:39], v[34:35], v[42:43] op_sel_hi:[0,1]
	v_cvt_pk_bf16_f32 v36, v36, v37
	v_cvt_pk_bf16_f32 v37, v38, v39
	v_pk_mul_f32 v[50:51], v[34:35], v[142:143] op_sel_hi:[0,1]
	global_store_dwordx2 v[48:49], v[36:37], off offset:64
	v_pk_mul_f32 v[36:37], v[34:35], v[44:45] op_sel_hi:[0,1]
	v_pk_mul_f32 v[34:35], v[34:35], v[46:47] op_sel_hi:[0,1]
	v_cvt_pk_bf16_f32 v50, v50, v51
	v_cvt_pk_bf16_f32 v51, v66, v67
	v_cvt_pk_bf16_f32 v36, v36, v37
	v_cvt_pk_bf16_f32 v37, v34, v35
	global_store_dwordx2 v[48:49], v[50:51], off
	global_store_dwordx2 v[48:49], v[36:37], off offset:96
	s_and_saveexec_b64 s[28:29], vcc
	s_cbranch_execz .LBB0_527
	v_log_f32_e32 v33, v33
	v_ashrrev_i32_e32 v53, 31, v52
	v_lshlrev_b64 v[34:35], 5, v[52:53]
	v_lshl_add_u64 v[34:35], s[40:41], 0, v[34:35]
	v_fmac_f32_e32 v32, 0x3f317218, v33
	global_store_dword v[34:35], v32, off
.LBB0_527:
	s_or_b64 exec, exec, s[28:29]
	s_waitcnt vmcnt(5)
	v_mfma_f32_16x16x32_bf16 v[8:11], v[8:11], v[4:7], 0
	v_add_u32_e32 v32, s51, v54
	v_lshlrev_b32_e32 v32, s90, v32
	v_add_u32_e32 v66, s91, v32
	s_waitcnt vmcnt(4)
	v_mfma_f32_16x16x32_bf16 v[8:11], v[12:15], v[0:3], v[8:11]
	ds_read_b128 v[12:15], v132
	ds_read_b128 v[32:35], v132 offset:64
	v_mul_f32_e32 v182, v55, v70
	v_mul_f32_e32 v177, v55, v71
	v_mul_f32_e32 v176, v55, v72
	v_mul_f32_e32 v175, v55, v73
	v_mul_f32_e32 v174, v55, v74
	v_mul_f32_e32 v173, v55, v75
	s_waitcnt lgkmcnt(1)
	v_mfma_f32_16x16x32_bf16 v[12:15], v[12:15], v[4:7], 0
	v_mul_f32_e32 v172, v55, v76
	v_mul_f32_e32 v169, v55, v77
	v_mul_f32_e32 v168, v55, v78
	v_mul_f32_e32 v167, v55, v79
	v_mul_f32_e32 v166, v55, v80
	v_mul_f32_e32 v165, v55, v81
	v_mul_f32_e32 v164, v55, v82
	v_mul_f32_e32 v163, v55, v83
	v_mul_f32_e32 v162, v55, v84
	v_mul_f32_e32 v161, v55, v85
	v_mul_f32_e32 v160, v55, v86
	v_mul_f32_e32 v159, v55, v87
	v_mul_f32_e32 v158, v55, v88
	v_mul_f32_e32 v157, v55, v89
	v_mul_f32_e32 v156, v55, v90
	v_mul_f32_e32 v155, v55, v91
	v_mul_f32_e32 v154, v55, v92
	v_mul_f32_e32 v153, v55, v93
	v_mul_f32_e32 v152, v55, v94
	v_mul_f32_e32 v151, v55, v95
	v_mul_f32_e32 v150, v55, v96
	v_mul_f32_e32 v149, v55, v97
	v_mul_f32_e32 v148, v55, v98
	v_mul_f32_e32 v147, v55, v99
	v_mul_f32_e32 v146, v55, v100
	v_mul_f32_e32 v145, v55, v101
	v_mul_f32_e32 v144, v55, v102
	v_mul_f32_e32 v143, v55, v103
	v_mul_f32_e32 v142, v55, v104
	v_mul_f32_e32 v67, v55, v105
	s_waitcnt lgkmcnt(0)
	v_mfma_f32_16x16x32_bf16 v[52:55], v[32:35], v[0:3], v[12:15]
	ds_read_b128 v[32:35], v133 offset:64
	s_and_b64 s[20:21], s[2:3], s[20:21]
	s_and_b64 s[26:27], s[0:1], s[26:27]
	ds_read_b128 v[12:15], v133
	s_waitcnt lgkmcnt(0)
	v_mfma_f32_16x16x32_bf16 v[12:15], v[12:15], v[4:7], 0
	ds_read_b128 v[178:181], v138 offset:64
	v_mfma_f32_16x16x32_bf16 v[48:51], v[32:35], v[0:3], v[12:15]
	ds_read_b128 v[32:35], v134 offset:64
	s_nop 4
	ds_read_b128 v[12:15], v134
	s_waitcnt lgkmcnt(0)
	v_mfma_f32_16x16x32_bf16 v[12:15], v[12:15], v[4:7], 0
	v_sub_f32_e32 v48, v48, v168
	v_sub_f32_e32 v49, v49, v167
	v_sub_f32_e32 v50, v50, v166
	v_mfma_f32_16x16x32_bf16 v[44:47], v[32:35], v[0:3], v[12:15]
	ds_read_b128 v[32:35], v135 offset:64
	v_sub_f32_e32 v51, v51, v165
	s_nop 1
	ds_read_b128 v[12:15], v135
	s_waitcnt lgkmcnt(0)
	v_mfma_f32_16x16x32_bf16 v[12:15], v[12:15], v[4:7], 0
	s_nop 0
	v_sub_f32_e32 v44, v44, v164
	v_sub_f32_e32 v45, v45, v163
	v_sub_f32_e32 v46, v46, v162
	v_mfma_f32_16x16x32_bf16 v[40:43], v[32:35], v[0:3], v[12:15]
	ds_read_b128 v[32:35], v136 offset:64
	v_sub_f32_e32 v47, v47, v161
	s_nop 0
	ds_read_b128 v[12:15], v136
	s_waitcnt lgkmcnt(0)
	v_mfma_f32_16x16x32_bf16 v[12:15], v[12:15], v[4:7], 0
	s_nop 1
	v_sub_f32_e32 v40, v40, v160
	v_sub_f32_e32 v41, v41, v159
	v_sub_f32_e32 v42, v42, v158
	v_mfma_f32_16x16x32_bf16 v[36:39], v[32:35], v[0:3], v[12:15]
	ds_read_b128 v[32:35], v137 offset:64
	v_sub_f32_e32 v43, v43, v157
	s_nop 0
	ds_read_b128 v[12:15], v137
	s_waitcnt lgkmcnt(0)
	v_mfma_f32_16x16x32_bf16 v[12:15], v[12:15], v[4:7], 0
	s_nop 1
	v_sub_f32_e32 v36, v36, v156
	v_sub_f32_e32 v37, v37, v155
	v_sub_f32_e32 v38, v38, v154
	v_mfma_f32_16x16x32_bf16 v[32:35], v[32:35], v[0:3], v[12:15]
	v_sub_f32_e32 v39, v39, v153
	s_nop 1
	ds_read_b128 v[12:15], v138
	s_waitcnt lgkmcnt(0)
	v_mfma_f32_16x16x32_bf16 v[12:15], v[12:15], v[4:7], 0
	s_nop 1
	v_sub_f32_e32 v32, v32, v152
	v_sub_f32_e32 v33, v33, v151
	v_sub_f32_e32 v34, v34, v150
	v_mfma_f32_16x16x32_bf16 v[12:15], v[178:181], v[0:3], v[12:15]
	ds_read_b128 v[178:181], v139
	v_sub_f32_e32 v35, v35, v149
	s_waitcnt lgkmcnt(0)
	v_mfma_f32_16x16x32_bf16 v[4:7], v[178:181], v[4:7], 0
	ds_read_b128 v[178:181], v139 offset:64
	s_nop 2
	v_sub_f32_e32 v12, v12, v148
	v_sub_f32_e32 v13, v13, v147
	s_waitcnt lgkmcnt(0)
	v_mfma_f32_16x16x32_bf16 v[0:3], v[178:181], v[0:3], v[4:7]
	s_nop 2
	v_sub_f32_e32 v6, v9, v177
	v_cndmask_b32_e64 v6, v141, v6, s[20:21]
	s_and_b64 s[20:21], s[4:5], s[22:23]
	v_sub_f32_e32 v7, v10, v176
	v_sub_f32_e32 v4, v8, v182
	v_cndmask_b32_e64 v7, v141, v7, s[20:21]
	s_and_b64 s[20:21], s[6:7], s[24:25]
	v_sub_f32_e32 v8, v11, v175
	v_cndmask_b32_e64 v8, v141, v8, s[20:21]
	s_add_i32 s20, s89, s52
	v_or_b32_e32 v9, s20, v68
	v_cmp_gt_i32_e64 s[20:21], s88, v9
	v_sub_f32_e32 v10, v52, v174
	v_or_b32_e32 v11, 1, v9
	v_cndmask_b32_e64 v10, v141, v10, s[20:21]
	v_cmp_gt_i32_e64 s[20:21], s88, v11
	v_sub_f32_e32 v11, v53, v173
	v_or_b32_e32 v52, 2, v9
	v_cndmask_b32_e64 v11, v141, v11, s[20:21]
	v_cmp_gt_i32_e64 s[20:21], s88, v52
	v_sub_f32_e32 v52, v54, v172
	v_or_b32_e32 v9, 3, v9
	v_cndmask_b32_e64 v52, v141, v52, s[20:21]
	v_cmp_gt_i32_e64 s[20:21], s88, v9
	v_sub_f32_e32 v9, v55, v169
	v_cndmask_b32_e64 v4, v141, v4, s[26:27]
	v_cndmask_b32_e64 v9, v141, v9, s[20:21]
	s_add_i32 s20, s89, s53
	v_or_b32_e32 v53, s20, v68
	v_cmp_gt_i32_e64 s[20:21], s88, v53
	v_or_b32_e32 v54, 1, v53
	v_max_f32_e32 v5, 0xf149f2ca, v4
	v_cndmask_b32_e64 v48, v141, v48, s[20:21]
	v_cmp_gt_i32_e64 s[20:21], s88, v54
	v_or_b32_e32 v54, 2, v53
	v_or_b32_e32 v53, 3, v53
	v_cndmask_b32_e64 v49, v141, v49, s[20:21]
	v_cmp_gt_i32_e64 s[20:21], s88, v54
	v_max3_f32 v5, v5, v6, v7
	v_max3_f32 v5, v5, v8, v10
	v_cndmask_b32_e64 v50, v141, v50, s[20:21]
	v_cmp_gt_i32_e64 s[20:21], s88, v53
	v_max3_f32 v5, v5, v11, v52
	v_max3_f32 v5, v5, v9, v48
	v_cndmask_b32_e64 v51, v141, v51, s[20:21]
	s_add_i32 s20, s89, s60
	v_or_b32_e32 v53, s20, v68
	v_cmp_gt_i32_e64 s[20:21], s88, v53
	v_or_b32_e32 v54, 1, v53
	v_max3_f32 v5, v5, v49, v50
	v_cndmask_b32_e64 v44, v141, v44, s[20:21]
	v_cmp_gt_i32_e64 s[20:21], s88, v54
	v_or_b32_e32 v54, 2, v53
	v_or_b32_e32 v53, 3, v53
	v_cndmask_b32_e64 v45, v141, v45, s[20:21]
	v_cmp_gt_i32_e64 s[20:21], s88, v54
	v_max3_f32 v5, v5, v51, v44
	v_sub_f32_e32 v14, v14, v146
	v_cndmask_b32_e64 v46, v141, v46, s[20:21]
	v_cmp_gt_i32_e64 s[20:21], s88, v53
	v_max3_f32 v5, v5, v45, v46
	v_sub_f32_e32 v15, v15, v145
	v_cndmask_b32_e64 v47, v141, v47, s[20:21]
	s_add_i32 s20, s89, s61
	v_or_b32_e32 v53, s20, v68
	v_cmp_gt_i32_e64 s[20:21], s88, v53
	v_or_b32_e32 v54, 1, v53
	v_sub_f32_e32 v0, v0, v144
	v_cndmask_b32_e64 v40, v141, v40, s[20:21]
	v_cmp_gt_i32_e64 s[20:21], s88, v54
	v_or_b32_e32 v54, 2, v53
	v_or_b32_e32 v53, 3, v53
	v_cndmask_b32_e64 v41, v141, v41, s[20:21]
	v_cmp_gt_i32_e64 s[20:21], s88, v54
	v_max3_f32 v5, v5, v47, v40
	v_sub_f32_e32 v1, v1, v143
	v_cndmask_b32_e64 v42, v141, v42, s[20:21]
	v_cmp_gt_i32_e64 s[20:21], s88, v53
	v_max3_f32 v5, v5, v41, v42
	v_sub_f32_e32 v2, v2, v142
	v_cndmask_b32_e64 v43, v141, v43, s[20:21]
	s_add_i32 s20, s89, s74
	v_or_b32_e32 v53, s20, v68
	v_cmp_gt_i32_e64 s[20:21], s88, v53
	v_or_b32_e32 v54, 1, v53
	v_sub_f32_e32 v3, v3, v67
	v_cndmask_b32_e64 v36, v141, v36, s[20:21]
	v_cmp_gt_i32_e64 s[20:21], s88, v54
	v_or_b32_e32 v54, 2, v53
	v_or_b32_e32 v53, 3, v53
	v_cndmask_b32_e64 v37, v141, v37, s[20:21]
	v_cmp_gt_i32_e64 s[20:21], s88, v54
	v_max3_f32 v5, v5, v43, v36
	s_nop 0
	v_cndmask_b32_e64 v38, v141, v38, s[20:21]
	v_cmp_gt_i32_e64 s[20:21], s88, v53
	v_max3_f32 v5, v5, v37, v38
	s_nop 0
	v_cndmask_b32_e64 v39, v141, v39, s[20:21]
	s_add_i32 s20, s89, s75
	v_or_b32_e32 v53, s20, v68
	v_cmp_gt_i32_e64 s[20:21], s88, v53
	v_or_b32_e32 v54, 1, v53
	s_nop 0
	v_cndmask_b32_e64 v32, v141, v32, s[20:21]
	v_cmp_gt_i32_e64 s[20:21], s88, v54
	v_or_b32_e32 v54, 2, v53
	v_or_b32_e32 v53, 3, v53
	v_cndmask_b32_e64 v33, v141, v33, s[20:21]
	v_cmp_gt_i32_e64 s[20:21], s88, v54
	v_max3_f32 v5, v5, v39, v32
	s_nop 0
	v_cndmask_b32_e64 v34, v141, v34, s[20:21]
	v_cmp_gt_i32_e64 s[20:21], s88, v53
	v_max3_f32 v5, v5, v33, v34
	s_nop 0
	v_cndmask_b32_e64 v35, v141, v35, s[20:21]
	s_add_i32 s20, s89, s76
	v_or_b32_e32 v53, s20, v68
	v_cmp_gt_i32_e64 s[20:21], s88, v53
	v_or_b32_e32 v54, 1, v53
	s_add_i32 s89, s89, s77
	v_cndmask_b32_e64 v12, v141, v12, s[20:21]
	v_cmp_gt_i32_e64 s[20:21], s88, v54
	v_or_b32_e32 v54, 2, v53
	v_or_b32_e32 v53, 3, v53
	v_cndmask_b32_e64 v13, v141, v13, s[20:21]
	v_cmp_gt_i32_e64 s[20:21], s88, v54
	s_and_b64 s[20:21], s[8:9], s[20:21]
	v_max3_f32 v5, v5, v35, v12
	v_cndmask_b32_e64 v14, v141, v14, s[20:21]
	v_cmp_gt_i32_e64 s[20:21], s88, v53
	s_and_b64 s[20:21], s[10:11], s[20:21]
	v_or_b32_e32 v53, s89, v68
	v_cndmask_b32_e64 v15, v141, v15, s[20:21]
	v_cmp_gt_i32_e64 s[20:21], s88, v53
	s_and_b64 s[20:21], s[12:13], s[20:21]
	v_max3_f32 v5, v5, v13, v14
	v_cndmask_b32_e64 v54, v141, v0, s[20:21]
	v_max3_f32 v0, v5, v15, v54
	v_or_b32_e32 v5, 1, v53
	v_cmp_gt_i32_e64 s[20:21], s88, v5
	s_and_b64 s[20:21], s[14:15], s[20:21]
	v_or_b32_e32 v5, 2, v53
	v_cndmask_b32_e64 v1, v141, v1, s[20:21]
	v_cmp_gt_i32_e64 s[20:21], s88, v5
	s_and_b64 s[20:21], s[16:17], s[20:21]
	v_or_b32_e32 v5, 3, v53
	v_cndmask_b32_e64 v2, v141, v2, s[20:21]
	v_cmp_gt_i32_e64 s[20:21], s88, v5
	s_and_b64 s[20:21], s[18:19], s[20:21]
	v_max3_f32 v0, v0, v1, v2
	v_cndmask_b32_e64 v5, v141, v3, s[20:21]
	v_max3_f32 v0, v0, v5, s83
	ds_bpermute_b32 v3, v119, v0
	s_waitcnt lgkmcnt(0)
	v_max_f32_e32 v3, v3, v3
	v_max_f32_e32 v0, v0, v3
	ds_bpermute_b32 v3, v120, v0
	s_waitcnt lgkmcnt(0)
	v_max_f32_e32 v3, v3, v3
	v_max_f32_e32 v0, v0, v3
	v_sub_f32_e32 v3, v4, v0
	v_mul_f32_e32 v3, 0x3fb8aa3b, v3
	v_sub_f32_e32 v6, v6, v0
	v_exp_f32_e32 v4, v3
	v_mul_f32_e32 v6, 0x3fb8aa3b, v6
	v_sub_f32_e32 v7, v7, v0
	v_exp_f32_e32 v6, v6
	v_mul_f32_e32 v7, 0x3fb8aa3b, v7
	v_sub_f32_e32 v8, v8, v0
	v_exp_f32_e32 v7, v7
	v_mul_f32_e32 v8, 0x3fb8aa3b, v8
	v_sub_f32_e32 v10, v10, v0
	v_exp_f32_e32 v8, v8
	v_mul_f32_e32 v10, 0x3fb8aa3b, v10
	v_sub_f32_e32 v11, v11, v0
	v_add_f32_e32 v3, 0, v4
	v_exp_f32_e32 v10, v10
	v_mul_f32_e32 v11, 0x3fb8aa3b, v11
	v_sub_f32_e32 v52, v52, v0
	v_add_f32_e32 v3, v6, v3
	v_exp_f32_e32 v11, v11
	v_mul_f32_e32 v52, 0x3fb8aa3b, v52
	v_sub_f32_e32 v9, v9, v0
	v_add_f32_e32 v3, v7, v3
	v_exp_f32_e32 v52, v52
	v_mul_f32_e32 v9, 0x3fb8aa3b, v9
	v_sub_f32_e32 v48, v48, v0
	v_add_f32_e32 v3, v8, v3
	v_exp_f32_e32 v9, v9
	v_mul_f32_e32 v48, 0x3fb8aa3b, v48
	v_sub_f32_e32 v49, v49, v0
	v_add_f32_e32 v3, v10, v3
	v_exp_f32_e32 v48, v48
	v_mul_f32_e32 v49, 0x3fb8aa3b, v49
	v_sub_f32_e32 v50, v50, v0
	v_add_f32_e32 v3, v11, v3
	v_exp_f32_e32 v49, v49
	v_mul_f32_e32 v50, 0x3fb8aa3b, v50
	v_sub_f32_e32 v51, v51, v0
	v_add_f32_e32 v3, v52, v3
	v_exp_f32_e32 v50, v50
	v_mul_f32_e32 v51, 0x3fb8aa3b, v51
	v_sub_f32_e32 v44, v44, v0
	v_add_f32_e32 v3, v9, v3
	v_exp_f32_e32 v51, v51
	v_mul_f32_e32 v44, 0x3fb8aa3b, v44
	v_sub_f32_e32 v45, v45, v0
	v_add_f32_e32 v3, v48, v3
	v_exp_f32_e32 v44, v44
	v_mul_f32_e32 v45, 0x3fb8aa3b, v45
	v_sub_f32_e32 v46, v46, v0
	v_add_f32_e32 v3, v49, v3
	v_exp_f32_e32 v45, v45
	v_mul_f32_e32 v46, 0x3fb8aa3b, v46
	v_sub_f32_e32 v47, v47, v0
	v_add_f32_e32 v3, v50, v3
	v_exp_f32_e32 v46, v46
	v_mul_f32_e32 v47, 0x3fb8aa3b, v47
	v_sub_f32_e32 v40, v40, v0
	v_add_f32_e32 v3, v51, v3
	v_exp_f32_e32 v47, v47
	v_mul_f32_e32 v40, 0x3fb8aa3b, v40
	v_sub_f32_e32 v41, v41, v0
	v_add_f32_e32 v3, v44, v3
	v_exp_f32_e32 v40, v40
	v_mul_f32_e32 v41, 0x3fb8aa3b, v41
	v_sub_f32_e32 v42, v42, v0
	v_add_f32_e32 v3, v45, v3
	v_exp_f32_e32 v41, v41
	v_mul_f32_e32 v42, 0x3fb8aa3b, v42
	v_sub_f32_e32 v43, v43, v0
	v_add_f32_e32 v3, v46, v3
	v_exp_f32_e32 v42, v42
	v_mul_f32_e32 v43, 0x3fb8aa3b, v43
	v_sub_f32_e32 v36, v36, v0
	v_add_f32_e32 v3, v47, v3
	v_exp_f32_e32 v43, v43
	v_mul_f32_e32 v36, 0x3fb8aa3b, v36
	v_sub_f32_e32 v37, v37, v0
	v_add_f32_e32 v3, v40, v3
	v_exp_f32_e32 v36, v36
	v_mul_f32_e32 v37, 0x3fb8aa3b, v37
	v_sub_f32_e32 v38, v38, v0
	v_add_f32_e32 v3, v41, v3
	v_exp_f32_e32 v37, v37
	v_mul_f32_e32 v38, 0x3fb8aa3b, v38
	v_sub_f32_e32 v39, v39, v0
	v_add_f32_e32 v3, v42, v3
	v_exp_f32_e32 v38, v38
	v_mul_f32_e32 v39, 0x3fb8aa3b, v39
	v_sub_f32_e32 v32, v32, v0
	v_add_f32_e32 v3, v43, v3
	v_exp_f32_e32 v39, v39
	v_mul_f32_e32 v32, 0x3fb8aa3b, v32
	v_sub_f32_e32 v33, v33, v0
	v_sub_f32_e32 v12, v12, v0
	v_add_f32_e32 v3, v36, v3
	v_exp_f32_e32 v32, v32
	v_mul_f32_e32 v33, 0x3fb8aa3b, v33
	v_sub_f32_e32 v34, v34, v0
	v_mul_f32_e32 v12, 0x3fb8aa3b, v12
	v_add_f32_e32 v3, v37, v3
	v_exp_f32_e32 v33, v33
	v_mul_f32_e32 v34, 0x3fb8aa3b, v34
	v_sub_f32_e32 v35, v35, v0
	v_exp_f32_e32 v53, v12
	v_sub_f32_e32 v12, v13, v0
	v_add_f32_e32 v3, v38, v3
	v_exp_f32_e32 v34, v34
	v_mul_f32_e32 v35, 0x3fb8aa3b, v35
	v_mul_f32_e32 v12, 0x3fb8aa3b, v12
	v_add_f32_e32 v3, v39, v3
	v_exp_f32_e32 v35, v35
	v_exp_f32_e32 v55, v12
	v_sub_f32_e32 v12, v14, v0
	v_add_f32_e32 v3, v32, v3
	v_mul_f32_e32 v12, 0x3fb8aa3b, v12
	v_add_f32_e32 v3, v33, v3
	v_exp_f32_e32 v67, v12
	v_sub_f32_e32 v12, v15, v0
	v_sub_f32_e32 v2, v2, v0
	v_add_f32_e32 v3, v34, v3
	v_mul_f32_e32 v12, 0x3fb8aa3b, v12
	v_mul_f32_e32 v2, 0x3fb8aa3b, v2
	v_add_f32_e32 v3, v35, v3
	v_exp_f32_e32 v142, v12
	v_exp_f32_e32 v143, v2
	v_sub_f32_e32 v2, v5, v0
	v_cvt_pk_bf16_f32 v4, v4, v6
	v_cvt_pk_bf16_f32 v5, v7, v8
	v_cvt_pk_bf16_f32 v6, v10, v11
	v_cvt_pk_bf16_f32 v7, v52, v9
	v_add_f32_e32 v3, v53, v3
	v_add_f32_e32 v3, v55, v3
	v_mfma_f32_16x16x32_bf16 v[8:11], v[16:19], v[4:7], 0
	v_add_f32_e32 v3, v67, v3
	v_add_f32_e32 v12, v142, v3
	v_sub_f32_e32 v3, v54, v0
	v_mfma_f32_16x16x32_bf16 v[16:19], v[24:27], v[4:7], 0
	ds_read2_b64 v[24:27], v204 offset0:32 offset1:36
	v_mul_f32_e32 v3, 0x3fb8aa3b, v3
	v_sub_f32_e32 v1, v1, v0
	v_exp_f32_e32 v3, v3
	v_mul_f32_e32 v1, 0x3fb8aa3b, v1
	v_exp_f32_e32 v54, v1
	v_mul_f32_e32 v2, 0x3fb8aa3b, v2
	v_add_f32_e32 v12, v3, v12
	v_exp_f32_e32 v144, v2
	v_add_f32_e32 v1, v54, v12
	v_mfma_f32_16x16x32_bf16 v[12:15], v[20:23], v[4:7], 0
	v_cvt_pk_bf16_f32 v20, v48, v49
	v_cvt_pk_bf16_f32 v21, v50, v51
	v_cvt_pk_bf16_f32 v22, v44, v45
	v_cvt_pk_bf16_f32 v23, v46, v47
	v_mfma_f32_16x16x32_bf16 v[4:7], v[28:31], v[4:7], 0
	v_sub_f32_e32 v2, 0xf149f2ca, v0
	v_mul_f32_e32 v2, 0x3fb8aa3b, v2
	v_exp_f32_e32 v145, v2
	s_waitcnt lgkmcnt(0)
	v_mfma_f32_16x16x32_bf16 v[8:11], v[24:27], v[20:23], v[8:11]
	ds_read2_b64 v[24:27], v205 offset0:32 offset1:36
	v_add_f32_e32 v1, v143, v1
	s_waitcnt lgkmcnt(0)
	v_mfma_f32_16x16x32_bf16 v[12:15], v[24:27], v[20:23], v[12:15]
	ds_read2_b64 v[24:27], v206 offset0:32 offset1:36
	v_add_f32_e32 v1, v144, v1
	s_waitcnt lgkmcnt(0)
	v_mfma_f32_16x16x32_bf16 v[16:19], v[24:27], v[20:23], v[16:19]
	ds_read2_b64 v[24:27], v207 offset0:32 offset1:36
	v_add_f32_e32 v1, v145, v1
	s_waitcnt lgkmcnt(0)
	v_mfma_f32_16x16x32_bf16 v[4:7], v[24:27], v[20:23], v[4:7]
	ds_read2_b64 v[24:27], v208 offset0:32 offset1:36
	v_cvt_pk_bf16_f32 v20, v40, v41
	v_cvt_pk_bf16_f32 v21, v42, v43
	v_cvt_pk_bf16_f32 v22, v36, v37
	v_cvt_pk_bf16_f32 v23, v38, v39
	v_add_f32_e32 v1, v145, v1
	v_add_f32_e32 v1, v145, v1
	s_waitcnt lgkmcnt(0)
	v_mfma_f32_16x16x32_bf16 v[8:11], v[24:27], v[20:23], v[8:11]
	ds_read2_b64 v[24:27], v209 offset0:32 offset1:36
	v_add_f32_e32 v1, v145, v1
	s_waitcnt lgkmcnt(0)
	v_mfma_f32_16x16x32_bf16 v[12:15], v[24:27], v[20:23], v[12:15]
	ds_read2_b64 v[24:27], v210 offset0:32 offset1:36
	ds_bpermute_b32 v2, v119, v1
	s_waitcnt lgkmcnt(1)
	v_mfma_f32_16x16x32_bf16 v[16:19], v[24:27], v[20:23], v[16:19]
	ds_read2_b64 v[24:27], v211 offset0:32 offset1:36
	s_waitcnt lgkmcnt(1)
	v_add_f32_e32 v1, v1, v2
	s_waitcnt lgkmcnt(0)
	v_mfma_f32_16x16x32_bf16 v[4:7], v[24:27], v[20:23], v[4:7]
	ds_read2_b64 v[24:27], v212 offset0:32 offset1:36
	v_cvt_pk_bf16_f32 v20, v32, v33
	v_cvt_pk_bf16_f32 v21, v34, v35
	v_cvt_pk_bf16_f32 v22, v53, v55
	v_cvt_pk_bf16_f32 v23, v67, v142
	ds_bpermute_b32 v2, v120, v1
	s_waitcnt lgkmcnt(0)
	v_add_f32_e32 v1, v1, v2
	v_mfma_f32_16x16x32_bf16 v[8:11], v[24:27], v[20:23], v[8:11]
	ds_read2_b64 v[24:27], v213 offset0:32 offset1:36
	v_rcp_f32_e32 v2, v1
	s_waitcnt lgkmcnt(0)
	v_mfma_f32_16x16x32_bf16 v[12:15], v[24:27], v[20:23], v[12:15]
	ds_read2_b64 v[24:27], v214 offset0:32 offset1:36
	s_waitcnt lgkmcnt(0)
	v_mfma_f32_16x16x32_bf16 v[16:19], v[24:27], v[20:23], v[16:19]
	ds_read2_b64 v[24:27], v215 offset0:32 offset1:36
	s_waitcnt lgkmcnt(0)
	v_mfma_f32_16x16x32_bf16 v[4:7], v[24:27], v[20:23], v[4:7]
	v_cvt_pk_bf16_f32 v20, v3, v54
	ds_read2_b64 v[24:27], v216 offset0:32 offset1:36
	v_cvt_pk_bf16_f32 v22, v145, v145
	v_cvt_pk_bf16_f32 v21, v143, v144
	v_mov_b32_e32 v23, v22
	s_waitcnt lgkmcnt(0)
	s_nop 0
	v_mfma_f32_16x16x32_bf16 v[8:11], v[24:27], v[20:23], v[8:11]
	ds_read2_b64 v[24:27], v217 offset0:32 offset1:36
	s_waitcnt lgkmcnt(0)
	v_mfma_f32_16x16x32_bf16 v[12:15], v[24:27], v[20:23], v[12:15]
	ds_read2_b64 v[24:27], v218 offset0:32 offset1:36
	v_add_u32_e32 v3, v118, v110
	v_add_u32_e32 v3, 0xe000, v3
	s_waitcnt lgkmcnt(0)
	v_mfma_f32_16x16x32_bf16 v[16:19], v[24:27], v[20:23], v[16:19]
	ds_read2_b64 v[24:27], v3 offset0:32 offset1:36
	v_pk_mul_f32 v[8:9], v[8:9], v[2:3] op_sel_hi:[1,0]
	v_pk_mul_f32 v[10:11], v[10:11], v[2:3] op_sel_hi:[1,0]
	s_waitcnt lgkmcnt(0)
	v_mfma_f32_16x16x32_bf16 v[4:7], v[24:27], v[20:23], v[4:7]
	v_mad_i64_i32 v[20:21], s[20:21], v66, s82, v[64:65]
	v_cvt_pk_bf16_f32 v8, v8, v9
	v_cvt_pk_bf16_f32 v9, v10, v11
	global_store_dwordx2 v[20:21], v[8:9], off
	v_pk_mul_f32 v[8:9], v[12:13], v[2:3] op_sel_hi:[1,0]
	v_pk_mul_f32 v[10:11], v[14:15], v[2:3] op_sel_hi:[1,0]
	v_cvt_pk_bf16_f32 v8, v8, v9
	v_cvt_pk_bf16_f32 v9, v10, v11
	global_store_dwordx2 v[20:21], v[8:9], off offset:32
	v_pk_mul_f32 v[8:9], v[16:17], v[2:3] op_sel_hi:[1,0]
	v_pk_mul_f32 v[10:11], v[18:19], v[2:3] op_sel_hi:[1,0]
	v_pk_mul_f32 v[4:5], v[2:3], v[4:5] op_sel_hi:[0,1]
	v_pk_mul_f32 v[2:3], v[2:3], v[6:7] op_sel_hi:[0,1]
	v_cvt_pk_bf16_f32 v8, v8, v9
	v_cvt_pk_bf16_f32 v9, v10, v11
	v_cvt_pk_bf16_f32 v4, v4, v5
	v_cvt_pk_bf16_f32 v5, v2, v3
	global_store_dwordx2 v[20:21], v[8:9], off offset:64
	global_store_dwordx2 v[20:21], v[4:5], off offset:96
	s_and_saveexec_b64 s[20:21], vcc
	s_cbranch_execz .LBB0_522
	v_log_f32_e32 v1, v1
	v_ashrrev_i32_e32 v67, 31, v66
	v_lshlrev_b64 v[2:3], 5, v[66:67]
	v_lshl_add_u64 v[2:3], s[40:41], 0, v[2:3]
	v_fmac_f32_e32 v0, 0x3f317218, v1
	global_store_dword v[2:3], v0, off
	s_branch .LBB0_522

.LBB0_642:
	s_lshl_b32 s12, s12, 5
	s_and_b32 s20, s12, 0x60
	s_mov_b64 s[12:13], 0x80
	s_add_i32 m0, s25, 0x18000
	v_lshl_add_u64 v[0:1], v[0:1], 0, s[12:13]
	s_lshl_b32 s17, s15, 13
	global_load_lds_dwordx4 v[0:1], off
	v_lshl_add_u64 v[0:1], v[2:3], 0, s[12:13]
	s_add_i32 m0, s25, 0x1a000
	s_add_i32 s45, s25, 0x8000
	s_add_i32 s46, s25, 0xa000
	global_load_lds_dwordx4 v[0:1], off
	v_lshl_add_u64 v[0:1], v[6:7], 0, s[12:13]
	s_mov_b32 m0, s45
	s_add_u32 s18, s28, 0x40080
	global_load_lds_dwordx4 v[0:1], off
	v_lshl_add_u64 v[0:1], v[4:5], 0, s[12:13]
	s_mov_b32 m0, s46
	s_addc_u32 s19, s29, 0
	global_load_lds_dwordx4 v[0:1], off
	s_add_i32 m0, s25, 0x1c000
	v_lshl_add_u64 v[0:1], s[18:19], 0, v[142:143]
	global_load_lds_dwordx4 v[0:1], off
	v_lshl_add_u64 v[0:1], s[18:19], 0, v[146:147]
	s_add_i32 m0, s25, 0x1e000
	s_cmpk_lt_u32 s14, 0x100
	global_load_lds_dwordx4 v[0:1], off
	s_waitcnt vmcnt(8)
	s_barrier
	s_sext_i32_i8 s49, s0
	v_lshl_or_b32 v152, s15, 6, v172
	s_cselect_b64 s[14:15], -1, 0
	s_sub_i32 s0, 64, s1
	s_min_i32 s0, s0, 8
	s_abs_i32 s18, s0
	v_cvt_f32_u32_e32 v2, s18
	v_lshlrev_b32_e32 v1, 2, v172
	v_lshl_or_b32 v0, v172, 6, v182
	v_and_b32_e32 v1, 32, v1
	v_bitop3_b32 v0, v0, s17, v1 bitop3:0xde
	v_rcp_iflag_f32_e32 v1, v2
	v_lshl_or_b32 v154, s20, 7, v183
	v_or_b32_e32 v155, s20, v181
	s_sub_i32 s20, 0, s18
	v_mul_f32_e32 v1, 0x4f7ffffe, v1
	v_cvt_u32_f32_e32 v1, v1
	s_abs_i32 s19, s16
	s_xor_b32 s17, s16, s0
	s_ashr_i32 s17, s17, 31
	v_readfirstlane_b32 s21, v1
	s_mul_i32 s20, s20, s21
	s_mul_hi_u32 s20, s21, s20
	s_add_i32 s21, s21, s20
	s_mul_hi_u32 s20, s19, s21
	s_mul_i32 s21, s20, s18
	s_sub_i32 s19, s19, s21
	s_add_i32 s21, s20, 1
	s_sub_i32 s22, s19, s18
	s_cmp_ge_u32 s19, s18
	s_cselect_b32 s20, s21, s20
	s_cselect_b32 s19, s22, s19
	s_add_i32 s21, s20, 1
	s_cmp_ge_u32 s19, s18
	v_lshlrev_b32_e32 v1, 8, v171
	s_cselect_b32 s18, s21, s20
	v_and_b32_e32 v1, 0x38000, v1
	v_lshlrev_b32_e32 v2, 11, v175
	s_xor_b32 s18, s18, s17
	v_or3_b32 v1, v179, v1, v2
	s_sub_i32 s17, s18, s17
	v_add_u32_e32 v128, v1, v173
	v_lshlrev_b32_e32 v1, 4, v180
	s_waitcnt vmcnt(6)
	s_mul_i32 s0, s17, s0
	v_and_b32_e32 v1, 0x78000, v1
	s_sub_i32 s0, s16, s0
	v_mov_b32_e32 v131, 0
	v_or3_b32 v1, v179, v1, v2
	s_add_i32 s47, 0, 0x10000
	s_add_i32 s48, 0, 0x14000
	s_add_i32 s16, s1, s0
	s_add_i32 s18, s17, 4
	v_mov_b32_e32 v129, v131
	v_add_u32_e32 v132, v1, v173
	v_mov_b32_e32 v133, v131
	s_mov_b64 s[34:35], -1
	v_add_u32_e32 v156, s47, v154
	v_add_u32_e32 v157, s48, v154
	v_add_u32_e32 v158, 0, v0
	s_barrier
	s_branch .LBB0_645

.LBB0_656:
	s_lshl_b32 s12, s12, 5
	s_and_b32 s18, s12, 0x60
	s_mov_b64 s[12:13], 0x80
	s_add_i32 m0, s25, 0x18000
	v_lshl_add_u64 v[6:7], v[6:7], 0, s[12:13]
	s_lshl_b32 s15, s14, 13
	global_load_lds_dwordx4 v[6:7], off
	v_lshl_add_u64 v[4:5], v[4:5], 0, s[12:13]
	s_add_i32 m0, s25, 0x1a000
	s_add_i32 s45, s25, 0x8000
	s_add_i32 s46, s25, 0xa000
	global_load_lds_dwordx4 v[4:5], off
	v_lshl_add_u64 v[0:1], v[0:1], 0, s[12:13]
	s_mov_b32 m0, s45
	s_add_u32 s16, s28, 0x20080
	global_load_lds_dwordx4 v[0:1], off
	v_lshl_add_u64 v[0:1], v[2:3], 0, s[12:13]
	s_mov_b32 m0, s46
	s_addc_u32 s17, s29, 0
	global_load_lds_dwordx4 v[0:1], off
	s_add_i32 m0, s25, 0x1c000
	v_lshl_add_u64 v[0:1], s[16:17], 0, v[150:151]
	global_load_lds_dwordx4 v[0:1], off
	v_lshl_add_u64 v[0:1], s[16:17], 0, v[154:155]
	s_add_i32 m0, s25, 0x1e000
	v_lshlrev_b32_e32 v2, 10, v175
	global_load_lds_dwordx4 v[0:1], off
	s_waitcnt vmcnt(8)
	s_barrier
	v_lshlrev_b32_e32 v1, 2, v172
	v_lshl_or_b32 v0, v172, 6, v182
	v_and_b32_e32 v1, 32, v1
	v_bitop3_b32 v0, v0, s15, v1 bitop3:0xde
	v_lshlrev_b32_e32 v1, 7, v171
	v_and_b32_e32 v1, 0x1c000, v1
	v_or3_b32 v1, v179, v1, v2
	v_add_u32_e32 v156, v1, v173
	v_lshlrev_b32_e32 v1, 3, v180
	s_waitcnt vmcnt(6)
	s_cmpk_lt_u32 s3, 0x100
	v_and_b32_e32 v1, 0x3c000, v1
	v_lshl_or_b32 v184, s14, 6, v172
	v_lshl_or_b32 v185, s18, 7, v183
	s_cselect_b64 s[14:15], -1, 0
	v_or3_b32 v1, v179, v1, v2
	s_add_i32 s47, 0, 0x10000
	s_add_i32 s48, 0, 0x14000
	s_sext_i32_i8 s49, s2
	v_or_b32_e32 v186, s18, v181
	v_mov_b32_e32 v157, v151
	v_add_u32_e32 v158, v1, v173
	v_mov_b32_e32 v159, v151
	v_mov_b64_e32 v[160:161], 0x100
	v_mov_b64_e32 v[162:163], 0xff
	v_add_u32_e32 v187, s47, v185
	v_add_u32_e32 v188, s48, v185
	v_add_u32_e32 v189, 0, v0
	s_barrier
	s_branch .LBB0_659

.LBB0_676:
	s_lshl_b32 s10, s10, 5
	s_and_b32 s16, s10, 0x60
	s_mov_b64 s[10:11], 0x80
	s_add_i32 m0, s29, 0x18000
	v_lshl_add_u64 v[0:1], v[0:1], 0, s[10:11]
	s_lshl_b32 s13, s12, 13
	global_load_lds_dwordx4 v[0:1], off
	v_lshl_add_u64 v[0:1], v[2:3], 0, s[10:11]
	s_add_i32 m0, s29, 0x1a000
	s_add_i32 s44, s29, 0x8000
	s_add_i32 s45, s29, 0xa000
	global_load_lds_dwordx4 v[0:1], off
	v_lshl_add_u64 v[0:1], v[6:7], 0, s[10:11]
	s_mov_b32 m0, s44
	s_add_u32 s14, s34, 0x40080
	global_load_lds_dwordx4 v[0:1], off
	v_lshl_add_u64 v[0:1], v[4:5], 0, s[10:11]
	s_mov_b32 m0, s45
	s_addc_u32 s15, s35, 0
	global_load_lds_dwordx4 v[0:1], off
	s_add_i32 m0, s29, 0x1c000
	v_lshl_add_u64 v[0:1], s[14:15], 0, v[142:143]
	global_load_lds_dwordx4 v[0:1], off
	v_lshl_add_u64 v[0:1], s[14:15], 0, v[146:147]
	s_add_i32 m0, s29, 0x1e000
	v_lshlrev_b32_e32 v2, 11, v175
	global_load_lds_dwordx4 v[0:1], off
	s_waitcnt vmcnt(8)
	s_barrier
	v_lshlrev_b32_e32 v1, 2, v172
	v_lshl_or_b32 v0, v172, 6, v182
	v_and_b32_e32 v1, 32, v1
	v_bitop3_b32 v0, v0, s13, v1 bitop3:0xde
	v_lshlrev_b32_e32 v1, 8, v171
	v_and_b32_e32 v1, 0x38000, v1
	v_or3_b32 v1, v179, v1, v2
	v_add_u32_e32 v128, v1, v173
	v_lshlrev_b32_e32 v1, 4, v180
	s_waitcnt vmcnt(6)
	s_cmpk_lt_u32 s1, 0x100
	v_and_b32_e32 v1, 0x78000, v1
	v_lshl_or_b32 v150, s12, 6, v172
	v_lshl_or_b32 v151, s16, 7, v183
	s_cselect_b64 s[12:13], -1, 0
	v_mov_b32_e32 v129, 0
	v_or3_b32 v1, v179, v1, v2
	s_add_i32 s46, 0, 0x10000
	s_add_i32 s47, 0, 0x14000
	s_sext_i32_i8 s48, s0
	v_or_b32_e32 v152, s16, v181
	v_add_u32_e32 v130, v1, v173
	v_mov_b32_e32 v131, v129
	v_mov_b64_e32 v[132:133], 0x100
	v_mov_b64_e32 v[134:135], 0xff
	v_add_u32_e32 v153, s46, v151
	v_add_u32_e32 v154, s47, v151
	v_add_u32_e32 v155, 0, v0
	s_mov_b64 s[14:15], 0x48000
	s_mov_b64 s[16:17], 0x50000
	s_mov_b64 s[18:19], 0x58000
	s_barrier
	s_branch .LBB0_679

.LBB0_748:
	s_lshl_b32 s12, s12, 5
	s_and_b32 s16, s12, 0x60
	s_mov_b64 s[12:13], 0x80
	v_readlane_b32 s22, v246, 48
	s_add_i32 m0, s31, 0x18000
	v_lshl_add_u64 v[0:1], v[0:1], 0, s[12:13]
	s_lshl_b32 s15, s14, 13
	s_lshl_b32 s20, s16, 7
	s_ashr_i32 s47, s22, 31
	global_load_lds_dwordx4 v[0:1], off
	v_lshl_add_u64 v[0:1], v[2:3], 0, s[12:13]
	s_add_i32 m0, s31, 0x1a000
	s_add_i32 s48, s31, 0x8000
	s_add_i32 s49, s31, 0xa000
	global_load_lds_dwordx4 v[0:1], off
	v_lshl_add_u64 v[0:1], v[6:7], 0, s[12:13]
	s_mov_b32 m0, s48
	s_add_u32 s18, s36, 0x40080
	global_load_lds_dwordx4 v[0:1], off
	v_lshl_add_u64 v[0:1], v[4:5], 0, s[12:13]
	s_mov_b32 m0, s49
	s_addc_u32 s19, s37, 0
	global_load_lds_dwordx4 v[0:1], off
	s_add_i32 m0, s31, 0x1c000
	v_lshl_add_u64 v[0:1], s[18:19], 0, v[128:129]
	global_load_lds_dwordx4 v[0:1], off
	v_lshl_add_u64 v[0:1], s[18:19], 0, v[130:131]
	s_add_i32 m0, s31, 0x1e000
	s_sext_i32_i8 s53, s2
	global_load_lds_dwordx4 v[0:1], off
	s_waitcnt vmcnt(8)
	s_barrier
	v_bfe_u32 v0, v171, 4, 2
	v_lshlrev_b32_e32 v1, 4, v0
	v_lshlrev_b32_e32 v2, 6, v171
	s_movk_i32 s2, 0x3c0
	v_and_or_b32 v2, v2, s2, v1
	v_lshl_or_b32 v182, v0, 2, s16
	v_lshlrev_b32_e32 v0, 8, v171
	v_bitop3_b32 v181, s20, v2, v180 bitop3:0xf6
	v_and_b32_e32 v0, 0x38000, v0
	v_lshlrev_b32_e32 v2, 11, v175
	v_or3_b32 v0, v168, v0, v2
	v_lshlrev_b32_e32 v3, 2, v172
	v_add_u32_e32 v132, v0, v173
	v_lshlrev_b32_e32 v0, 4, v169
	v_lshl_or_b32 v1, v172, 6, v1
	v_and_b32_e32 v3, 32, v3
	s_waitcnt vmcnt(6)
	s_cmpk_lt_u32 s3, 0x100
	v_and_b32_e32 v0, 0x78000, v0
	v_lshl_or_b32 v179, s14, 6, v172
	v_bitop3_b32 v1, v1, s15, v3 bitop3:0xde
	s_cselect_b64 s[14:15], -1, 0
	v_mov_b32_e32 v133, 0
	v_or3_b32 v0, v168, v0, v2
	s_add_i32 s51, 0, 0x10000
	s_add_i32 s52, 0, 0x14000
	s_mov_b32 s50, s22
	v_add_u32_e32 v134, v0, v173
	v_mov_b32_e32 v135, v133
	v_mov_b64_e32 v[136:137], 0x100
	v_mov_b64_e32 v[138:139], 0xff
	v_add_u32_e32 v183, s51, v181
	v_add_u32_e32 v184, s52, v181
	v_add_u32_e32 v185, 0, v1
	s_mov_b32 s16, 0x3f9837f0
	s_mov_b64 s[18:19], 0xa0000
	s_mov_b64 s[20:21], 0xb0000
	v_readlane_b32 s23, v246, 49
	s_barrier
	s_branch .LBB0_751

.LBB0_770:
	s_sext_i32_i8 s4, s0
	v_lshlrev_b32_e32 v8, 6, v171
	v_and_b32_e32 v9, 48, v171
	s_movk_i32 s0, 0x3c0
	v_lshlrev_b32_e32 v10, 2, v172
	s_mov_b64 s[14:15], 0x80
	v_and_or_b32 v8, v8, s0, v9
	s_and_b32 s5, s31, 3
	v_lshl_or_b32 v9, v172, 6, v9
	s_lshl_b32 s0, s34, 13
	v_and_b32_e32 v10, 32, v10
	s_add_i32 m0, s11, 0x18000
	v_lshl_add_u64 v[0:1], v[0:1], 0, s[14:15]
	s_lshl_b32 s39, s34, 6
	v_bitop3_b32 v9, v9, s0, v10 bitop3:0xde
	s_lshl_b32 s0, s5, 12
	global_load_lds_dwordx4 v[0:1], off
	v_lshl_add_u64 v[0:1], v[2:3], 0, s[14:15]
	s_add_i32 m0, s11, 0x1a000
	s_add_i32 s41, s11, 0x8000
	s_add_i32 s42, s11, 0xa000
	global_load_lds_dwordx4 v[0:1], off
	v_lshl_add_u64 v[0:1], v[6:7], 0, s[14:15]
	s_mov_b32 m0, s41
	s_add_u32 s2, s24, 0x40080
	global_load_lds_dwordx4 v[0:1], off
	v_lshl_add_u64 v[0:1], v[4:5], 0, s[14:15]
	s_mov_b32 m0, s42
	s_addc_u32 s3, s25, 0
	global_load_lds_dwordx4 v[0:1], off
	s_add_i32 m0, s11, 0x1c000
	v_lshl_add_u64 v[0:1], s[2:3], 0, v[128:129]
	global_load_lds_dwordx4 v[0:1], off
	v_lshl_add_u64 v[0:1], s[2:3], 0, v[130:131]
	s_add_i32 m0, s11, 0x1e000
	v_lshlrev_b32_e32 v2, 11, v175
	global_load_lds_dwordx4 v[0:1], off
	s_waitcnt vmcnt(8)
	s_barrier
	v_lshlrev_b32_e32 v0, 8, v171
	v_and_b32_e32 v0, 0x38000, v0
	v_or3_b32 v0, v168, v0, v2
	v_bitop3_b32 v145, s0, v8, v180 bitop3:0xf6
	s_mov_b64 s[0:1], 0x40080
	v_add_u32_e32 v0, v0, v173
	v_mov_b32_e32 v1, 0
	v_lshl_add_u64 v[132:133], v[0:1], 0, s[0:1]
	v_lshlrev_b32_e32 v0, 4, v169
	v_and_b32_e32 v0, 0x78000, v0
	s_waitcnt vmcnt(6)
	v_or3_b32 v0, v168, v0, v2
	v_add_u32_e32 v0, v0, v173
	v_lshrrev_b32_e32 v144, 2, v171
	v_or_b32_e32 v179, s39, v172
	v_lshl_add_u64 v[134:135], v[0:1], 0, s[0:1]
	v_mov_b64_e32 v[136:137], 0x100
	v_mov_b64_e32 v[138:139], 0xff
	s_add_i32 s43, 0, 0x10000
	s_add_i32 s44, 0, 0x14000
	v_add_u32_e32 v146, 0, v9
	v_mov_b32_e32 v0, v1
	v_mov_b32_e32 v2, v1
	v_mov_b32_e32 v3, v1
	v_mov_b32_e32 v4, v1
	v_mov_b32_e32 v5, v1
	v_mov_b32_e32 v6, v1
	v_mov_b32_e32 v7, v1
	v_mov_b32_e32 v16, v1
	v_mov_b32_e32 v17, v1
	v_mov_b32_e32 v18, v1
	v_mov_b32_e32 v19, v1
	v_mov_b32_e32 v20, v1
	v_mov_b32_e32 v21, v1
	v_mov_b32_e32 v22, v1
	v_mov_b32_e32 v23, v1
	v_mov_b32_e32 v32, v1
	v_mov_b32_e32 v33, v1
	v_mov_b32_e32 v34, v1
	v_mov_b32_e32 v35, v1
	v_mov_b32_e32 v36, v1
	v_mov_b32_e32 v37, v1
	v_mov_b32_e32 v38, v1
	v_mov_b32_e32 v39, v1
	v_mov_b32_e32 v48, v1
	v_mov_b32_e32 v49, v1
	v_mov_b32_e32 v50, v1
	v_mov_b32_e32 v51, v1
	v_mov_b32_e32 v52, v1
	v_mov_b32_e32 v53, v1
	v_mov_b32_e32 v54, v1
	v_mov_b32_e32 v55, v1
	v_mov_b32_e32 v8, v1
	v_mov_b32_e32 v9, v1
	v_mov_b32_e32 v10, v1
	v_mov_b32_e32 v11, v1
	v_mov_b32_e32 v12, v1
	v_mov_b32_e32 v13, v1
	v_mov_b32_e32 v14, v1
	v_mov_b32_e32 v15, v1
	v_mov_b32_e32 v24, v1
	v_mov_b32_e32 v25, v1
	v_mov_b32_e32 v26, v1
	v_mov_b32_e32 v27, v1
	v_mov_b32_e32 v28, v1
	v_mov_b32_e32 v29, v1
	v_mov_b32_e32 v30, v1
	v_mov_b32_e32 v31, v1
	v_mov_b32_e32 v40, v1
	v_mov_b32_e32 v41, v1
	v_mov_b32_e32 v42, v1
	v_mov_b32_e32 v43, v1
	v_mov_b32_e32 v44, v1
	v_mov_b32_e32 v45, v1
	v_mov_b32_e32 v46, v1
	v_mov_b32_e32 v47, v1
	v_mov_b32_e32 v56, v1
	v_mov_b32_e32 v57, v1
	v_mov_b32_e32 v58, v1
	v_mov_b32_e32 v59, v1
	v_mov_b32_e32 v60, v1
	v_mov_b32_e32 v61, v1
	v_mov_b32_e32 v62, v1
	v_mov_b32_e32 v63, v1
	v_mov_b32_e32 v92, v1
	v_mov_b32_e32 v93, v1
	v_mov_b32_e32 v94, v1
	v_mov_b32_e32 v95, v1
	v_mov_b32_e32 v104, v1
	v_mov_b32_e32 v105, v1
	v_mov_b32_e32 v106, v1
	v_mov_b32_e32 v107, v1
	v_mov_b32_e32 v80, v1
	v_mov_b32_e32 v81, v1
	v_mov_b32_e32 v82, v1
	v_mov_b32_e32 v83, v1
	v_mov_b32_e32 v88, v1
	v_mov_b32_e32 v89, v1
	v_mov_b32_e32 v90, v1
	v_mov_b32_e32 v91, v1
	v_mov_b32_e32 v64, v1
	v_mov_b32_e32 v65, v1
	v_mov_b32_e32 v66, v1
	v_mov_b32_e32 v67, v1
	v_mov_b32_e32 v72, v1
	v_mov_b32_e32 v73, v1
	v_mov_b32_e32 v74, v1
	v_mov_b32_e32 v75, v1
	v_mov_b32_e32 v68, v1
	v_mov_b32_e32 v69, v1
	v_mov_b32_e32 v70, v1
	v_mov_b32_e32 v71, v1
	v_mov_b32_e32 v76, v1
	v_mov_b32_e32 v77, v1
	v_mov_b32_e32 v78, v1
	v_mov_b32_e32 v79, v1
	v_mov_b32_e32 v120, v1
	v_mov_b32_e32 v121, v1
	v_mov_b32_e32 v122, v1
	v_mov_b32_e32 v123, v1
	v_mov_b32_e32 v124, v1
	v_mov_b32_e32 v125, v1
	v_mov_b32_e32 v126, v1
	v_mov_b32_e32 v127, v1
	v_mov_b32_e32 v112, v1
	v_mov_b32_e32 v113, v1
	v_mov_b32_e32 v114, v1
	v_mov_b32_e32 v115, v1
	v_mov_b32_e32 v116, v1
	v_mov_b32_e32 v117, v1
	v_mov_b32_e32 v118, v1
	v_mov_b32_e32 v119, v1
	v_mov_b32_e32 v84, v1
	v_mov_b32_e32 v85, v1
	v_mov_b32_e32 v86, v1
	v_mov_b32_e32 v87, v1
	v_mov_b32_e32 v108, v1
	v_mov_b32_e32 v109, v1
	v_mov_b32_e32 v110, v1
	v_mov_b32_e32 v111, v1
	v_mov_b32_e32 v96, v1
	v_mov_b32_e32 v97, v1
	v_mov_b32_e32 v98, v1
	v_mov_b32_e32 v99, v1
	v_mov_b32_e32 v100, v1
	v_mov_b32_e32 v101, v1
	v_mov_b32_e32 v102, v1
	v_mov_b32_e32 v103, v1
	s_barrier

.LBB0_936:
	s_lshl_b32 s8, s8, 5
	s_and_b32 s14, s8, 0x60
	s_mov_b64 s[8:9], 0x80
	v_readlane_b32 s16, v246, 48
	s_add_i32 m0, s21, 0x18000
	v_lshl_add_u64 v[6:7], v[6:7], 0, s[8:9]
	s_ashr_i32 s36, s16, 31
	s_lshl_b32 s11, s10, 13
	s_lshl_b32 s15, s14, 7
	global_load_lds_dwordx4 v[6:7], off
	v_lshl_add_u64 v[4:5], v[4:5], 0, s[8:9]
	s_add_i32 m0, s21, 0x1a000
	s_add_i32 s37, s21, 0x8000
	s_add_i32 s38, s21, 0xa000
	global_load_lds_dwordx4 v[4:5], off
	v_lshl_add_u64 v[0:1], v[0:1], 0, s[8:9]
	s_mov_b32 m0, s37
	s_add_u32 s12, s24, 0x40080
	global_load_lds_dwordx4 v[0:1], off
	v_lshl_add_u64 v[0:1], v[2:3], 0, s[8:9]
	s_mov_b32 m0, s38
	s_addc_u32 s13, s25, 0
	global_load_lds_dwordx4 v[0:1], off
	s_add_i32 m0, s21, 0x1c000
	v_lshl_add_u64 v[0:1], s[12:13], 0, v[130:131]
	global_load_lds_dwordx4 v[0:1], off
	v_lshl_add_u64 v[0:1], s[12:13], 0, v[134:135]
	s_add_i32 m0, s21, 0x1e000
	s_sext_i32_i16 s43, s0
	global_load_lds_dwordx4 v[0:1], off
	s_waitcnt vmcnt(8)
	s_barrier
	v_lshlrev_b32_e32 v0, 1, v9
	v_lshlrev_b32_e32 v1, 6, v171
	s_movk_i32 s0, 0x3c0
	v_and_or_b32 v1, v1, s0, v0
	v_and_b32_e32 v2, 32, v174
	v_lshl_or_b32 v0, v172, 6, v0
	v_bitop3_b32 v145, s15, v1, v2 bitop3:0xf6
	v_lshlrev_b32_e32 v1, 8, v171
	v_bitop3_b32 v0, v0, s11, v2 bitop3:0xde
	v_and_b32_e32 v1, 0x38000, v1
	v_lshlrev_b32_e32 v2, 11, v175
	v_or3_b32 v1, v8, v1, v2
	v_add_u32_e32 v136, v1, v173
	v_lshlrev_b32_e32 v1, 4, v10
	s_waitcnt vmcnt(6)
	s_cmpk_lt_u32 s1, 0x100
	v_and_b32_e32 v1, 0x78000, v1
	v_lshl_or_b32 v144, s10, 6, v172
	s_cselect_b64 s[10:11], -1, 0
	v_or3_b32 v1, v8, v1, v2
	s_add_i32 s40, 0, 0x10000
	s_add_i32 s41, 0, 0x14000
	s_mov_b32 s39, s16
	v_or_b32_e32 v146, s14, v9
	v_mov_b32_e32 v137, v131
	v_add_u32_e32 v138, v1, v173
	v_mov_b32_e32 v139, v131
	v_mov_b64_e32 v[140:141], 0x580
	v_mov_b64_e32 v[142:143], 0x57f
	v_add_u32_e32 v147, s40, v145
	v_add_u32_e32 v148, s41, v145
	v_add_u32_e32 v149, 0, v0
	s_movk_i32 s42, 0x1600
	v_readlane_b32 s17, v246, 49
	s_barrier
	s_branch .LBB0_939

.LBB0_1004:
	s_lshl_b32 s5, s5, 5
	s_mov_b64 s[16:17], 0x80
	s_and_b32 s5, s5, 0x60
	v_readlane_b32 s24, v246, 48
	s_add_i32 m0, s41, 0x18000
	v_lshl_add_u64 v[0:1], v[0:1], 0, s[16:17]
	s_lshl_b32 s20, s3, 13
	s_lshl_b32 s22, s5, 7
	s_ashr_i32 s46, s24, 31
	global_load_lds_dwordx4 v[0:1], off
	v_lshl_add_u64 v[0:1], v[2:3], 0, s[16:17]
	s_add_i32 m0, s41, 0x1a000
	s_add_i32 s47, s41, 0x8000
	s_add_i32 s48, s41, 0xa000
	global_load_lds_dwordx4 v[0:1], off
	v_lshl_add_u64 v[0:1], v[6:7], 0, s[16:17]
	s_mov_b32 m0, s47
	s_add_u32 s18, s34, 0xb0080
	global_load_lds_dwordx4 v[0:1], off
	v_lshl_add_u64 v[0:1], v[4:5], 0, s[16:17]
	s_mov_b32 m0, s48
	s_addc_u32 s19, s35, 0
	global_load_lds_dwordx4 v[0:1], off
	s_add_i32 m0, s41, 0x1c000
	v_lshl_add_u64 v[0:1], s[18:19], 0, v[128:129]
	global_load_lds_dwordx4 v[0:1], off
	v_lshl_add_u64 v[0:1], s[18:19], 0, v[130:131]
	s_add_i32 m0, s41, 0x1e000
	s_sext_i32_i8 s55, s4
	global_load_lds_dwordx4 v[0:1], off
	s_waitcnt vmcnt(8)
	s_barrier
	v_bfe_u32 v0, v171, 4, 2
	v_lshlrev_b32_e32 v1, 4, v0
	v_lshlrev_b32_e32 v2, 6, v171
	s_movk_i32 s4, 0x3c0
	v_lshlrev_b32_e32 v3, 2, v172
	v_and_or_b32 v2, v2, s4, v1
	v_lshl_or_b32 v1, v172, 6, v1
	v_and_b32_e32 v3, 32, v3
	s_waitcnt vmcnt(6)
	s_cmpk_lt_u32 s2, 0x100
	v_readlane_b32 s25, v246, 49
	v_bitop3_b32 v1, v1, s20, v3 bitop3:0xde
	v_bitop3_b32 v147, s22, v2, v146 bitop3:0xf6
	s_cselect_b64 s[18:19], -1, 0
	v_mov_b32_e32 v133, 0
	s_add_i32 s50, 0, 0x10000
	s_add_i32 s51, 0, 0x14000
	v_lshl_or_b32 v145, s3, 6, v172
	s_mov_b32 s49, s24
	v_lshl_or_b32 v148, v0, 2, s5
	v_add3_u32 v132, v143, v142, v173
	v_add3_u32 v134, v144, v142, v173
	v_mov_b32_e32 v135, v133
	v_mov_b64_e32 v[136:137], 0x100
	v_mov_b64_e32 v[138:139], 0xff
	v_add_u32_e32 v149, s50, v147
	v_add_u32_e32 v150, s51, v147
	v_add_u32_e32 v151, 0, v1
	s_mov_b32 s20, 0x3f9837f0
	s_mov_b64 s[22:23], 0x80000
	s_mov_b64 s[24:25], 0x90000
	s_mov_b64 s[26:27], 0xa0000
	s_barrier
	s_branch .LBB0_1007

.LBB0_1030:
	s_sext_i32_i8 s10, s0
	v_lshlrev_b32_e32 v8, 6, v171
	v_and_b32_e32 v9, 48, v171
	s_movk_i32 s0, 0x3c0
	v_lshlrev_b32_e32 v10, 2, v172
	s_mov_b64 s[14:15], 0x80
	v_and_or_b32 v8, v8, s0, v9
	s_and_b32 s11, s26, 3
	v_lshl_or_b32 v9, v172, 6, v9
	s_lshl_b32 s0, s27, 13
	v_and_b32_e32 v10, 32, v10
	s_add_i32 m0, s29, 0x18000
	v_lshl_add_u64 v[0:1], v[0:1], 0, s[14:15]
	s_lshl_b32 s35, s27, 6
	v_bitop3_b32 v9, v9, s0, v10 bitop3:0xde
	s_lshl_b32 s0, s11, 12
	global_load_lds_dwordx4 v[0:1], off
	v_lshl_add_u64 v[0:1], v[2:3], 0, s[14:15]
	s_add_i32 m0, s29, 0x1a000
	s_add_i32 s37, s29, 0x8000
	s_add_i32 s38, s29, 0xa000
	global_load_lds_dwordx4 v[0:1], off
	v_lshl_add_u64 v[0:1], v[6:7], 0, s[14:15]
	s_mov_b32 m0, s37
	s_add_u32 s2, s18, 0xb0080
	global_load_lds_dwordx4 v[0:1], off
	v_lshl_add_u64 v[0:1], v[4:5], 0, s[14:15]
	s_mov_b32 m0, s38
	s_addc_u32 s3, s19, 0
	global_load_lds_dwordx4 v[0:1], off
	s_add_i32 m0, s29, 0x1c000
	v_lshl_add_u64 v[0:1], s[2:3], 0, v[128:129]
	global_load_lds_dwordx4 v[0:1], off
	v_lshl_add_u64 v[0:1], s[2:3], 0, v[130:131]
	s_add_i32 m0, s29, 0x1e000
	v_bitop3_b32 v146, s0, v8, v146 bitop3:0xf6
	global_load_lds_dwordx4 v[0:1], off
	s_waitcnt vmcnt(8)
	s_barrier
	s_mov_b64 s[0:1], 0xb0080
	s_waitcnt vmcnt(6)
	v_add3_u32 v0, v143, v142, v173
	v_mov_b32_e32 v1, 0
	v_lshl_add_u64 v[132:133], v[0:1], 0, s[0:1]
	v_add3_u32 v0, v144, v142, v173
	v_lshrrev_b32_e32 v145, 2, v171
	v_or_b32_e32 v162, s35, v172
	v_lshl_add_u64 v[134:135], v[0:1], 0, s[0:1]
	v_mov_b64_e32 v[136:137], 0x100
	v_mov_b64_e32 v[138:139], 0xff
	s_add_i32 s39, 0, 0x10000
	s_add_i32 s40, 0, 0x14000
	v_add_u32_e32 v144, 0, v9
	v_mov_b32_e32 v0, v1
	v_mov_b32_e32 v2, v1
	v_mov_b32_e32 v3, v1
	v_mov_b32_e32 v4, v1
	v_mov_b32_e32 v5, v1
	v_mov_b32_e32 v6, v1
	v_mov_b32_e32 v7, v1
	v_mov_b32_e32 v16, v1
	v_mov_b32_e32 v17, v1
	v_mov_b32_e32 v18, v1
	v_mov_b32_e32 v19, v1
	v_mov_b32_e32 v20, v1
	v_mov_b32_e32 v21, v1
	v_mov_b32_e32 v22, v1
	v_mov_b32_e32 v23, v1
	v_mov_b32_e32 v32, v1
	v_mov_b32_e32 v33, v1
	v_mov_b32_e32 v34, v1
	v_mov_b32_e32 v35, v1
	v_mov_b32_e32 v36, v1
	v_mov_b32_e32 v37, v1
	v_mov_b32_e32 v38, v1
	v_mov_b32_e32 v39, v1
	v_mov_b32_e32 v48, v1
	v_mov_b32_e32 v49, v1
	v_mov_b32_e32 v50, v1
	v_mov_b32_e32 v51, v1
	v_mov_b32_e32 v52, v1
	v_mov_b32_e32 v53, v1
	v_mov_b32_e32 v54, v1
	v_mov_b32_e32 v55, v1
	v_mov_b32_e32 v8, v1
	v_mov_b32_e32 v9, v1
	v_mov_b32_e32 v10, v1
	v_mov_b32_e32 v11, v1
	v_mov_b32_e32 v12, v1
	v_mov_b32_e32 v13, v1
	v_mov_b32_e32 v14, v1
	v_mov_b32_e32 v15, v1
	v_mov_b32_e32 v24, v1
	v_mov_b32_e32 v25, v1
	v_mov_b32_e32 v26, v1
	v_mov_b32_e32 v27, v1
	v_mov_b32_e32 v28, v1
	v_mov_b32_e32 v29, v1
	v_mov_b32_e32 v30, v1
	v_mov_b32_e32 v31, v1
	v_mov_b32_e32 v40, v1
	v_mov_b32_e32 v41, v1
	v_mov_b32_e32 v42, v1
	v_mov_b32_e32 v43, v1
	v_mov_b32_e32 v44, v1
	v_mov_b32_e32 v45, v1
	v_mov_b32_e32 v46, v1
	v_mov_b32_e32 v47, v1
	v_mov_b32_e32 v56, v1
	v_mov_b32_e32 v57, v1
	v_mov_b32_e32 v58, v1
	v_mov_b32_e32 v59, v1
	v_mov_b32_e32 v60, v1
	v_mov_b32_e32 v61, v1
	v_mov_b32_e32 v62, v1
	v_mov_b32_e32 v63, v1
	v_mov_b32_e32 v64, v1
	v_mov_b32_e32 v65, v1
	v_mov_b32_e32 v66, v1
	v_mov_b32_e32 v67, v1
	v_mov_b32_e32 v68, v1
	v_mov_b32_e32 v69, v1
	v_mov_b32_e32 v70, v1
	v_mov_b32_e32 v71, v1
	v_mov_b32_e32 v72, v1
	v_mov_b32_e32 v73, v1
	v_mov_b32_e32 v74, v1
	v_mov_b32_e32 v75, v1
	v_mov_b32_e32 v84, v1
	v_mov_b32_e32 v85, v1
	v_mov_b32_e32 v86, v1
	v_mov_b32_e32 v87, v1
	v_mov_b32_e32 v80, v1
	v_mov_b32_e32 v81, v1
	v_mov_b32_e32 v82, v1
	v_mov_b32_e32 v83, v1
	v_mov_b32_e32 v88, v1
	v_mov_b32_e32 v89, v1
	v_mov_b32_e32 v90, v1
	v_mov_b32_e32 v91, v1
	v_mov_b32_e32 v108, v1
	v_mov_b32_e32 v109, v1
	v_mov_b32_e32 v110, v1
	v_mov_b32_e32 v111, v1
	v_mov_b32_e32 v112, v1
	v_mov_b32_e32 v113, v1
	v_mov_b32_e32 v114, v1
	v_mov_b32_e32 v115, v1
	v_mov_b32_e32 v76, v1
	v_mov_b32_e32 v77, v1
	v_mov_b32_e32 v78, v1
	v_mov_b32_e32 v79, v1
	v_mov_b32_e32 v96, v1
	v_mov_b32_e32 v97, v1
	v_mov_b32_e32 v98, v1
	v_mov_b32_e32 v99, v1
	v_mov_b32_e32 v92, v1
	v_mov_b32_e32 v93, v1
	v_mov_b32_e32 v94, v1
	v_mov_b32_e32 v95, v1
	v_mov_b32_e32 v104, v1
	v_mov_b32_e32 v105, v1
	v_mov_b32_e32 v106, v1
	v_mov_b32_e32 v107, v1
	v_mov_b32_e32 v100, v1
	v_mov_b32_e32 v101, v1
	v_mov_b32_e32 v102, v1
	v_mov_b32_e32 v103, v1
	v_mov_b32_e32 v116, v1
	v_mov_b32_e32 v117, v1
	v_mov_b32_e32 v118, v1
	v_mov_b32_e32 v119, v1
	v_mov_b32_e32 v120, v1
	v_mov_b32_e32 v121, v1
	v_mov_b32_e32 v122, v1
	v_mov_b32_e32 v123, v1
	v_mov_b32_e32 v124, v1
	v_mov_b32_e32 v125, v1
	v_mov_b32_e32 v126, v1
	v_mov_b32_e32 v127, v1
	s_barrier
